# mixC: second query tile Q and first-half K fragments requested under the first tile softmax / P V (registers v128-v195 free there)
# baseline (speedup 1.0000x reference)
; __device__ __forceinline__ void mixC_mfma_unit(const bf16* Z, bf16* Yc, const float* rpb, LAS unsigned char* lds, int u, int S, int tid) {
;     ...
; #pragma unroll
;     for (int qt = 0; qt < 2; ++qt) {
;     const int qr = 4 * np + 2 * qt + (w >> 2), cb = w & 3, qc = cb * 16 + n;
;     int rs = qr - 4; rs = rs < 0 ? 0 : (rs > rows - 8 ? rows - 8 : rs);
;     int cbs = cb * 16 - 8; cbs = cbs < 0 ? 0 : (cbs > 32 ? 32 : cbs);
;     int cs = qc - 8; cs = cs < 0 ? 0 : (cs > 48 ? 48 : cs);
;     const int tokc = seq0 + qr * 64 + qc;
;     const bf16* qp = Z + (size_t)tokc * NZ + 6144 + h * 64;
;     const bf16x8_t qf0 = *(const bf16x8_t*)(qp + 8 * q), qf1 = *(const bf16x8_t*)(qp + 32 + 8 * q);
;     f32x4 s[16];
; #pragma unroll
;     for (int hf = 0; hf < 2; ++hf) {
;         bf16x8_t kf[8][2];
; #pragma unroll
;         for (int tt = 0; tt < 8; ++tt) { const int t = 8 * hf + tt;
;             const bf16* kp = zk + (size_t)((rs + (t >> 1)) * 64 + cbs + (t & 1) * 16 + n) * NZ + 8 * q;
;             kf[tt][0] = *(const bf16x8_t*)kp; kf[tt][1] = *(const bf16x8_t*)(kp + 32); }
; #pragma unroll
;         for (int tt = 0; tt < 8; ++tt) {
;             f32x4 a = {0.f, 0.f, 0.f, 0.f};
;             a = __builtin_amdgcn_mfma_f32_16x16x32_bf16(kf[tt][0], qf0, a, 0, 0, 0);
;             s[8 * hf + tt] = __builtin_amdgcn_mfma_f32_16x16x32_bf16(kf[tt][1], qf1, a, 0, 0, 0);
;         }
.LBB0_269:
	s_or_b64 exec, exec, s[20:21]
	v_ashrrev_i32_e32 v3, 8, v1
	v_lshrrev_b32_e32 v77, 2, v1
	v_and_b32_e32 v2, 15, v1
	v_add_u32_e32 v88, s22, v3
	v_and_b32_e32 v3, 48, v77
	v_or_b32_e32 v94, v3, v2
	v_med3_u32 v3, v3, 8, 40
	v_add_u32_e32 v85, -8, v3
	v_bfe_u32 v48, v1, 4, 2
	v_or_b32_e32 v89, s4, v94
	v_add_u32_e32 v83, v85, v2
	v_add_u32_e32 v2, -4, v88
	v_readlane_b32 s21, v255, 10
	v_lshlrev_b32_e32 v72, 4, v48
	v_mov_b32_e32 v73, v0
	v_min_i32_e32 v2, s21, v2
	v_cmp_lt_i32_e32 vcc, 3, v88
	v_lshl_add_u32 v76, v88, 6, v89
	v_mov_b64_e32 v[74:75], s[12:13]
	v_lshl_add_u64 v[70:71], s[16:17], 0, v[72:73]
	s_lshl_b32 s70, s3, 1
	v_cndmask_b32_e32 v95, 0, v2, vcc
	v_mad_i64_i32 v[2:3], s[16:17], v76, s66, v[74:75]
	v_lshl_add_u64 v[2:3], v[2:3], 0, s[70:71]
	v_lshl_add_u64 v[30:31], v[2:3], 0, v[72:73]
	s_movk_i32 s20, 0x3000
	v_lshlrev_b32_e32 v101, 6, v95
	v_add_co_u32_e32 v2, vcc, s20, v30
	v_add_u32_e32 v6, v101, v83
	s_nop 0
	v_addc_co_u32_e32 v3, vcc, 0, v31, vcc
	v_mad_i64_i32 v[26:27], s[16:17], v6, s66, v[70:71]
	s_waitcnt lgkmcnt(0)
	s_barrier
	global_load_dwordx4 v[2:5], v[2:3], off
	v_add_u32_e32 v84, 16, v83
	global_load_dwordx4 v[6:9], v[26:27], off
	v_add_u32_e32 v10, v101, v84
	v_mad_i64_i32 v[32:33], s[16:17], v10, s66, v[70:71]
	global_load_dwordx4 v[10:13], v[32:33], off
	v_add_u32_e32 v18, 64, v101
	v_add_u32_e32 v44, 0x80, v101
	v_add_u32_e32 v14, v18, v83
	v_add_u32_e32 v18, v18, v84
	v_add_u32_e32 v22, v44, v83
	v_mad_i64_i32 v[34:35], s[16:17], v14, s66, v[70:71]
	v_mad_i64_i32 v[38:39], s[16:17], v18, s66, v[70:71]
	v_mad_i64_i32 v[42:43], s[16:17], v22, s66, v[70:71]
	global_load_dwordx4 v[14:17], v[34:35], off
	global_load_dwordx4 v[18:21], v[38:39], off
	global_load_dwordx4 v[22:25], v[42:43], off
	s_nop 0
	global_load_dwordx4 v[26:29], v[26:27], off offset:64
	s_mov_b64 s[24:25], 0x3000
	v_lshl_add_u64 v[36:37], v[30:31], 0, s[24:25]
	global_load_dwordx4 v[30:33], v[32:33], off offset:64
	s_nop 0
	global_load_dwordx4 v[78:81], v[36:37], off offset:64
	s_nop 0
	global_load_dwordx4 v[34:37], v[34:35], off offset:64
	s_nop 0
	global_load_dwordx4 v[38:41], v[38:39], off offset:64
	v_add_u32_e32 v46, v44, v84
	v_mad_i64_i32 v[46:47], s[16:17], v46, s66, v[70:71]
	global_load_dwordx4 v[42:45], v[42:43], off offset:64
	v_add_u32_e32 v49, 0xc0, v101
	global_load_dwordx4 v[66:69], v[46:47], off
	v_add_u32_e32 v50, v49, v83
	global_load_dwordx4 v[102:105], v[46:47], off offset:64
	v_mad_i64_i32 v[46:47], s[16:17], v50, s66, v[70:71]
	v_add_u32_e32 v49, v49, v84
	global_load_dwordx4 v[106:109], v[46:47], off
	global_load_dwordx4 v[110:113], v[46:47], off offset:64
	v_mad_i64_i32 v[46:47], s[16:17], v49, s66, v[70:71]
	s_add_u32 s16, s90, s70
	s_addc_u32 s17, s91, 0
	s_waitcnt vmcnt(10)
	v_mfma_f32_16x16x32_bf16 v[22:25], v[22:25], v[2:5], 0
	v_mfma_f32_16x16x32_bf16 v[6:9], v[6:9], v[2:5], 0
	v_mfma_f32_16x16x32_bf16 v[10:13], v[10:13], v[2:5], 0
	s_waitcnt vmcnt(7)
	v_mfma_f32_16x16x32_bf16 v[62:65], v[26:29], v[78:81], v[6:9]
	v_lshlrev_b32_e32 v28, 3, v1
	v_lshlrev_b32_e32 v1, 2, v48
	v_mov_b32_e32 v27, v0
	s_nop 1
	global_load_dwordx4 v[6:9], v[46:47], off
	v_mfma_f32_16x16x32_bf16 v[58:61], v[30:33], v[78:81], v[10:13]
	v_lshlrev_b32_e32 v26, 3, v48
	v_add_u32_e32 v100, v85, v1
	v_and_or_b32 v1, v77, 3, v1
	global_load_dwordx4 v[10:13], v[46:47], off offset:64
	v_mfma_f32_16x16x32_bf16 v[14:17], v[14:17], v[2:5], 0
	v_add_u32_e32 v1, v85, v1
	v_ashrrev_i32_e32 v77, 31, v76
	v_mfma_f32_16x16x32_bf16 v[18:21], v[18:21], v[2:5], 0
	s_waitcnt vmcnt(8)
	v_mfma_f32_16x16x32_bf16 v[54:57], v[34:37], v[78:81], v[14:17]
	s_nop 2
	v_med3_u32 v14, v94, 8, 56
	v_add_u32_e32 v98, -8, v14
	v_add_u32_e32 v99, 8, v14
	v_and_b32_e32 v14, 64, v231
	s_waitcnt vmcnt(7)
	v_mfma_f32_16x16x32_bf16 v[50:53], v[38:41], v[78:81], v[18:21]
	s_nop 2
	v_add_u32_e32 v19, 64, v14
	s_waitcnt vmcnt(5)
	v_mfma_f32_16x16x32_bf16 v[14:17], v[66:69], v[2:5], 0
	v_xor_b32_e32 v18, 16, v231
	v_cmp_lt_i32_e32 vcc, v18, v19
	v_lshl_add_u64 v[66:67], s[16:17], 0, v[26:27]
	s_waitcnt vmcnt(4)
	v_mfma_f32_16x16x32_bf16 v[38:41], v[102:105], v[78:81], v[14:17]
	v_cndmask_b32_e32 v18, v231, v18, vcc
	v_lshlrev_b32_e32 v69, 2, v18
	s_nop 0
	v_xor_b32_e32 v14, 32, v231
	v_cmp_lt_i32_e32 vcc, v14, v19
	s_waitcnt vmcnt(1)
	v_mfma_f32_16x16x32_bf16 v[6:9], v[6:9], v[2:5], 0
	v_cndmask_b32_e32 v18, v231, v14, vcc
	v_lshlrev_b32_e32 v82, 2, v18
	v_mfma_f32_16x16x32_bf16 v[14:17], v[106:109], v[2:5], 0
	v_mfma_f32_16x16x32_bf16 v[34:37], v[110:113], v[78:81], v[14:17]
	v_mfma_f32_16x16x32_bf16 v[46:49], v[42:45], v[78:81], v[22:25]
	s_nop 5
	v_and_b32_e32 v14, 24, v28
	v_add_u32_e32 v68, 0, v14
	s_waitcnt vmcnt(0)
	v_mfma_f32_16x16x32_bf16 v[30:33], v[10:13], v[78:81], v[6:9]
	v_add_u32_e32 v10, 0x100, v101
	v_add_u32_e32 v14, 0x140, v101
	v_add_u32_e32 v26, 0x180, v101
	v_add_u32_e32 v44, 0x1c0, v101
	v_add_u32_e32 v6, v10, v83
	v_add_u32_e32 v10, v10, v84
	v_add_u32_e32 v15, v14, v83
	v_add_u32_e32 v18, v14, v84
	v_add_u32_e32 v22, v26, v83
	v_add_u32_e32 v26, v26, v84
	v_add_u32_e32 v45, v44, v83
	v_add_u32_e32 v44, v44, v84
	v_mad_i64_i32 v[42:43], s[16:17], v6, s66, v[70:71]
	v_mad_i64_i32 v[86:87], s[16:17], v10, s66, v[70:71]
	v_mad_i64_i32 v[92:93], s[16:17], v15, s66, v[70:71]
	v_mad_i64_i32 v[96:97], s[16:17], v18, s66, v[70:71]
	v_mad_i64_i32 v[118:119], s[16:17], v22, s66, v[70:71]
	v_mad_i64_i32 v[120:121], s[16:17], v26, s66, v[70:71]
	v_mad_i64_i32 v[122:123], s[16:17], v45, s66, v[70:71]
	v_mad_i64_i32 v[124:125], s[16:17], v44, s66, v[70:71]
	global_load_dwordx4 v[6:9], v[42:43], off
	global_load_dwordx4 v[10:13], v[86:87], off
	global_load_dwordx4 v[14:17], v[92:93], off
	global_load_dwordx4 v[18:21], v[96:97], off
	global_load_dwordx4 v[102:105], v[118:119], off
	global_load_dwordx4 v[106:109], v[120:121], off
	global_load_dwordx4 v[110:113], v[122:123], off
	global_load_dwordx4 v[114:117], v[124:125], off
	global_load_dwordx4 v[180:183], v[42:43], off offset:64
	global_load_dwordx4 v[184:187], v[86:87], off offset:64
	global_load_dwordx4 v[188:191], v[92:93], off offset:64
	global_load_dwordx4 v[192:195], v[96:97], off offset:64
	global_load_dwordx4 v[202:205], v[118:119], off offset:64
	global_load_dwordx4 v[206:209], v[120:121], off offset:64
	global_load_dwordx4 v[214:217], v[124:125], off offset:64
	global_load_dwordx4 v[210:213], v[122:123], off offset:64
	s_waitcnt vmcnt(15)
; #define LAS __attribute__((address_space(3)))
; __device__ __forceinline__ void mixC_mfma_unit(const bf16* Z, bf16* Yc, const float* rpb, LAS unsigned char* lds, int u, int S, int tid) {
;     ...
;     const int qr = 4 * np + 2 * qt + (w >> 2), cb = w & 3, qc = cb * 16 + n;
;     int rs = qr - 4; rs = rs < 0 ? 0 : (rs > rows - 8 ? rows - 8 : rs);
;     int cbs = cb * 16 - 8; cbs = cbs < 0 ? 0 : (cbs > 32 ? 32 : cbs);
;     int cs = qc - 8; cs = cs < 0 ? 0 : (cs > 48 ? 48 : cs);
;     const int tokc = seq0 + qr * 64 + qc;
;     const bf16* qp = Z + (size_t)tokc * NZ + 6144 + h * 64;
;     const bf16x8_t qf0 = *(const bf16x8_t*)(qp + 8 * q), qf1 = *(const bf16x8_t*)(qp + 32 + 8 * q);
;     f32x4 s[16];
; #pragma unroll
;     for (int hf = 0; hf < 2; ++hf) {
;         bf16x8_t kf[8][2];
; #pragma unroll
;         for (int tt = 0; tt < 8; ++tt) { const int t = 8 * hf + tt;
;             const bf16* kp = zk + (size_t)((rs + (t >> 1)) * 64 + cbs + (t & 1) * 16 + n) * NZ + 8 * q;
;             kf[tt][0] = *(const bf16x8_t*)kp; kf[tt][1] = *(const bf16x8_t*)(kp + 32); }
;     ...
;     const LAS float* rbp = (const LAS float*)(lds + C_ROWS * KPITCH);
;     float m = -1e30f;
; #pragma unroll
;     for (int t = 0; t < 16; ++t)
; #pragma unroll
;         for (int j = 0; j < 4; ++j) {
;             const int kr = rs + (t >> 1), kc = cbs + (t & 1) * 16 + 4 * q + j;
;             const bool valid = (kc >= cs) && (kc < cs + 16);
;             int dc = kc - qc + 15; dc = dc < 0 ? 0 : (dc > 30 ? 30 : dc);
;             const float sc = s[t][j] * 0.125f + rbp[(kr - qr + 7) * 31 + dc];
;             s[t][j] = valid ? sc : -1e30f; m = fmaxf(m, s[t][j]);
;         }
	v_mfma_f32_16x16x32_bf16 v[6:9], v[6:9], v[2:5], 0
	s_waitcnt vmcnt(14)
	v_mfma_f32_16x16x32_bf16 v[10:13], v[10:13], v[2:5], 0
	s_waitcnt vmcnt(13)
	v_mfma_f32_16x16x32_bf16 v[14:17], v[14:17], v[2:5], 0
	s_waitcnt vmcnt(12)
	v_mfma_f32_16x16x32_bf16 v[18:21], v[18:21], v[2:5], 0
	s_waitcnt vmcnt(11)
	v_mfma_f32_16x16x32_bf16 v[102:105], v[102:105], v[2:5], 0
	s_waitcnt vmcnt(10)
	v_mfma_f32_16x16x32_bf16 v[106:109], v[106:109], v[2:5], 0
	s_waitcnt vmcnt(9)
	v_mfma_f32_16x16x32_bf16 v[110:113], v[110:113], v[2:5], 0
	s_waitcnt vmcnt(8)
	v_mfma_f32_16x16x32_bf16 v[114:117], v[114:117], v[2:5], 0
	s_waitcnt vmcnt(7)
	v_mfma_f32_16x16x32_bf16 v[42:45], v[180:183], v[78:81], v[6:9]
	s_waitcnt vmcnt(6)
	v_mfma_f32_16x16x32_bf16 v[26:29], v[184:187], v[78:81], v[10:13]
	s_waitcnt vmcnt(5)
	v_mfma_f32_16x16x32_bf16 v[22:25], v[188:191], v[78:81], v[14:17]
	s_waitcnt vmcnt(4)
	v_mfma_f32_16x16x32_bf16 v[18:21], v[192:195], v[78:81], v[18:21]
	s_waitcnt vmcnt(3)
	v_mfma_f32_16x16x32_bf16 v[14:17], v[202:205], v[78:81], v[102:105]
	s_waitcnt vmcnt(2)
	v_mfma_f32_16x16x32_bf16 v[6:9], v[206:209], v[78:81], v[106:109]
	s_waitcnt vmcnt(1)
	v_mfma_f32_16x16x32_bf16 v[10:13], v[214:217], v[78:81], v[114:117]
	s_waitcnt vmcnt(0)
	v_mfma_f32_16x16x32_bf16 v[2:5], v[210:213], v[78:81], v[110:113]
	v_add_u32_e32 v219, 2, v88
	v_cmp_lt_i32_e32 vcc, 3, v219
	v_add_u32_e32 v226, -2, v88
	v_min_i32_e32 v226, s21, v226
	v_lshl_add_u32 v227, v219, 6, v89
	v_cndmask_b32_e32 v226, 0, v226, vcc
	v_lshlrev_b32_e32 v226, 6, v226
	v_mad_i64_i32 v[196:197], s[16:17], v227, s66, v[74:75]
	v_lshl_add_u64 v[196:197], v[196:197], 0, s[70:71]
	v_lshl_add_u64 v[196:197], v[196:197], 0, v[72:73]
	v_lshl_add_u64 v[196:197], v[196:197], 0, s[24:25]
	global_load_dwordx4 v[222:225], v[196:197], off
	global_load_dwordx4 v[176:179], v[196:197], off offset:64
	v_add_u32_e32 v219, v226, v83
	v_mad_i64_i32 v[196:197], s[16:17], v219, s66, v[70:71]
	global_load_dwordx4 v[128:131], v[196:197], off
	global_load_dwordx4 v[132:135], v[196:197], off offset:64
	v_add_u32_e32 v219, v226, v84
	v_mad_i64_i32 v[196:197], s[16:17], v219, s66, v[70:71]
	global_load_dwordx4 v[136:139], v[196:197], off
	global_load_dwordx4 v[140:143], v[196:197], off offset:64
	v_add_u32_e32 v227, 0x40, v226
	v_add_u32_e32 v219, v227, v83
	v_mad_i64_i32 v[196:197], s[16:17], v219, s66, v[70:71]
	global_load_dwordx4 v[144:147], v[196:197], off
	global_load_dwordx4 v[148:151], v[196:197], off offset:64
	v_add_u32_e32 v219, v227, v84
	v_mad_i64_i32 v[196:197], s[16:17], v219, s66, v[70:71]
	global_load_dwordx4 v[152:155], v[196:197], off
	global_load_dwordx4 v[156:159], v[196:197], off offset:64
	v_add_u32_e32 v227, 0x80, v226
	v_add_u32_e32 v219, v227, v83
	v_mad_i64_i32 v[196:197], s[16:17], v219, s66, v[70:71]
	global_load_dwordx4 v[160:163], v[196:197], off
	global_load_dwordx4 v[164:167], v[196:197], off offset:64
	v_add_u32_e32 v219, v227, v84
	v_mad_i64_i32 v[196:197], s[16:17], v219, s66, v[70:71]
	global_load_dwordx4 v[168:171], v[196:197], off
	global_load_dwordx4 v[172:175], v[196:197], off offset:64
	v_add_u32_e32 v227, 0xc0, v226
	v_add_u32_e32 v219, v227, v83
	v_mad_i64_i32 v[196:197], s[16:17], v219, s66, v[70:71]
	global_load_dwordx4 v[180:183], v[196:197], off
	global_load_dwordx4 v[184:187], v[196:197], off offset:64
	v_add_u32_e32 v219, v227, v84
	v_mad_i64_i32 v[196:197], s[16:17], v219, s66, v[70:71]
	global_load_dwordx4 v[188:191], v[196:197], off
	global_load_dwordx4 v[192:195], v[196:197], off offset:64
	v_sub_u32_e32 v78, v95, v88
	s_movk_i32 s4, 0x7c
	v_mul_lo_u32 v78, v78, s4
	s_add_i32 s3, 0, 0x18c00
	v_add_u32_e32 v101, s3, v78
	v_sub_u32_e32 v78, v100, v94
	v_med3_i32 v78, v78, -15, 15
	v_lshlrev_b32_e32 v85, 2, v78
	v_add_u32_e32 v110, v101, v85
	v_add_u32_e32 v78, 0x200, v110
	ds_read2_b32 v[78:79], v78 offset0:104 offset1:135
	v_cmp_ge_u32_e32 vcc, v100, v98
	v_cmp_lt_u32_e64 s[40:41], v100, v99
	s_and_b64 vcc, vcc, s[40:41]
	s_mov_b32 s15, 0xf149f2ca
	s_waitcnt lgkmcnt(0)
	v_fmamk_f32 v62, v62, 0x3e000000, v78
	v_cndmask_b32_e32 v96, v241, v62, vcc
	v_or_b32_e32 v62, 1, v100
	v_cmp_ge_u32_e64 s[40:41], v62, v98
	v_cmp_lt_u32_e64 s[42:43], v62, v99
	v_sub_u32_e32 v62, v62, v94
	v_med3_i32 v62, v62, -15, 15
	v_lshlrev_b32_e32 v78, 2, v62
	v_add_u32_e32 v111, v101, v78
	v_add_u32_e32 v62, 0x200, v111
	ds_read2_b32 v[80:81], v62 offset0:104 offset1:135
	s_and_b64 s[40:41], s[40:41], s[42:43]
	v_fmac_f32_e32 v79, 0x3e000000, v54
	s_waitcnt lgkmcnt(0)
	v_fmamk_f32 v62, v63, 0x3e000000, v80
	v_cndmask_b32_e64 v97, v241, v62, s[40:41]
	v_or_b32_e32 v62, 2, v100
	v_cmp_ge_u32_e64 s[42:43], v62, v98
	v_cmp_lt_u32_e64 s[44:45], v62, v99
	v_sub_u32_e32 v62, v62, v94
	v_med3_i32 v62, v62, -15, 15
	v_lshlrev_b32_e32 v80, 2, v62
	v_add_u32_e32 v112, v101, v80
	v_add_u32_e32 v62, 0x200, v112
	ds_read2_b32 v[62:63], v62 offset0:104 offset1:135
	s_and_b64 s[42:43], s[42:43], s[44:45]
	v_max3_f32 v87, v96, s15, v97
	v_fmac_f32_e32 v81, 0x3e000000, v55
	s_waitcnt lgkmcnt(0)
	v_fmamk_f32 v62, v64, 0x3e000000, v62
	v_or_b32_e32 v64, 3, v100
	v_cmp_ge_u32_e64 s[44:45], v64, v98
	v_cmp_lt_u32_e64 s[46:47], v64, v99
	v_sub_u32_e32 v64, v64, v94
	v_med3_i32 v64, v64, -15, 15
	v_lshlrev_b32_e32 v86, 2, v64
	v_add_u32_e32 v113, v101, v86
	v_add_u32_e32 v64, 0x200, v113
	ds_read2_b32 v[102:103], v64 offset0:104 offset1:135
	s_and_b64 s[44:45], s[44:45], s[46:47]
	v_cndmask_b32_e64 v62, v241, v62, s[42:43]
	v_fmac_f32_e32 v63, 0x3e000000, v56
	v_cndmask_b32_e64 v54, v241, v63, s[42:43]
	s_waitcnt lgkmcnt(0)
; __device__ __forceinline__ void mixC_mfma_unit(const bf16* Z, bf16* Yc, const float* rpb, LAS unsigned char* lds, int u, int S, int tid) {
;     ...
;     for (int t = 0; t < 16; ++t)
; #pragma unroll
;         for (int j = 0; j < 4; ++j) {
;             const int kr = rs + (t >> 1), kc = cbs + (t & 1) * 16 + 4 * q + j;
;             const bool valid = (kc >= cs) && (kc < cs + 16);
;             int dc = kc - qc + 15; dc = dc < 0 ? 0 : (dc > 30 ? 30 : dc);
;             const float sc = s[t][j] * 0.125f + rbp[(kr - qr + 7) * 31 + dc];
;             s[t][j] = valid ? sc : -1e30f; m = fmaxf(m, s[t][j]);
;         }
	v_fmamk_f32 v64, v65, 0x3e000000, v102
	v_cndmask_b32_e64 v64, v241, v64, s[44:45]
	v_max3_f32 v65, v87, v62, v64
	v_add_u32_e32 v87, 16, v100
	v_cmp_ge_u32_e64 s[46:47], v87, v98
	v_cmp_lt_u32_e64 s[48:49], v87, v99
	v_sub_u32_e32 v87, v87, v94
	v_med3_i32 v87, v87, -15, 15
	v_lshlrev_b32_e32 v87, 2, v87
	v_add_u32_e32 v102, v101, v87
	v_add_u32_e32 v92, 0x200, v102
	ds_read2_b32 v[104:105], v92 offset0:104 offset1:135
	v_add_u32_e32 v92, 17, v100
	s_and_b64 s[46:47], s[46:47], s[48:49]
	v_cmp_ge_u32_e64 s[48:49], v92, v98
	v_cmp_lt_u32_e64 s[50:51], v92, v99
	v_sub_u32_e32 v92, v92, v94
	v_med3_i32 v92, v92, -15, 15
	v_lshlrev_b32_e32 v92, 2, v92
	v_add_u32_e32 v114, v101, v92
	v_add_u32_e32 v93, 0x200, v114
	ds_read2_b32 v[106:107], v93 offset0:104 offset1:135
	s_waitcnt lgkmcnt(1)
	v_fmamk_f32 v58, v58, 0x3e000000, v104
	s_and_b64 s[48:49], s[48:49], s[50:51]
	v_cndmask_b32_e64 v58, v241, v58, s[46:47]
	v_fmac_f32_e32 v103, 0x3e000000, v57
	s_waitcnt lgkmcnt(0)
	v_fmamk_f32 v59, v59, 0x3e000000, v106
	v_cndmask_b32_e64 v59, v241, v59, s[48:49]
	v_max3_f32 v104, v65, v58, v59
	v_add_u32_e32 v65, 18, v100
	v_cmp_ge_u32_e64 s[50:51], v65, v98
	v_cmp_lt_u32_e64 s[52:53], v65, v99
	v_sub_u32_e32 v65, v65, v94
	v_med3_i32 v65, v65, -15, 15
	v_lshlrev_b32_e32 v93, 2, v65
	v_add_u32_e32 v116, v101, v93
	v_add_u32_e32 v65, 0x200, v116
	ds_read2_b32 v[108:109], v65 offset0:104 offset1:135
	s_and_b64 s[50:51], s[50:51], s[52:53]
	v_cndmask_b32_e64 v55, v241, v103, s[44:45]
	v_fmac_f32_e32 v105, 0x3e000000, v50
	v_fmac_f32_e32 v107, 0x3e000000, v51
	s_waitcnt lgkmcnt(0)
	v_fmamk_f32 v60, v60, 0x3e000000, v108
	v_cndmask_b32_e64 v65, v241, v60, s[50:51]
	v_add_u32_e32 v60, 19, v100
	v_cmp_ge_u32_e64 s[52:53], v60, v98
	v_cmp_lt_u32_e64 s[54:55], v60, v99
	v_sub_u32_e32 v60, v60, v94
	v_med3_i32 v60, v60, -15, 15
	v_lshlrev_b32_e32 v94, 2, v60
	v_add_u32_e32 v60, v101, v94
	v_add_u32_e32 v98, 0x200, v60
	ds_read2_b32 v[100:101], v98 offset0:104 offset1:135
	s_and_b64 s[52:53], s[52:53], s[54:55]
	v_cndmask_b32_e32 v99, v241, v79, vcc
	v_cndmask_b32_e64 v98, v241, v81, s[40:41]
	v_cndmask_b32_e64 v57, v241, v107, s[48:49]
	s_waitcnt lgkmcnt(0)
	v_fmamk_f32 v61, v61, 0x3e000000, v100
	v_cndmask_b32_e64 v100, v241, v61, s[52:53]
	v_max3_f32 v61, v104, v65, v100
	v_max3_f32 v61, v61, v99, v98
	v_max3_f32 v56, v61, v54, v55
	v_cndmask_b32_e64 v61, v241, v105, s[46:47]
	v_fmac_f32_e32 v109, 0x3e000000, v52
	v_fmac_f32_e32 v101, 0x3e000000, v53
	v_max3_f32 v56, v56, v61, v57
	v_cndmask_b32_e64 v51, v241, v109, s[50:51]
	v_cndmask_b32_e64 v50, v241, v101, s[52:53]
	v_max3_f32 v53, v56, v51, v50
	v_add_u32_e32 v56, 0x400, v110
	v_add_u32_e32 v63, 0x400, v111
	ds_read2_b32 v[104:105], v56 offset0:38 offset1:69
	ds_read2_b32 v[106:107], v63 offset0:38 offset1:69
	v_add_u32_e32 v81, 0x400, v113
	ds_read2_b32 v[110:111], v81 offset0:38 offset1:69
	v_add_u32_e32 v79, 0x400, v112
	s_waitcnt lgkmcnt(2)
	v_fmamk_f32 v46, v46, 0x3e000000, v104
	s_waitcnt lgkmcnt(1)
	v_fmamk_f32 v47, v47, 0x3e000000, v106
	v_cndmask_b32_e32 v46, v241, v46, vcc
	v_cndmask_b32_e64 v52, v241, v47, s[40:41]
	s_waitcnt lgkmcnt(0)
	v_fmamk_f32 v49, v49, 0x3e000000, v110
	v_max3_f32 v47, v53, v46, v52
	ds_read2_b32 v[108:109], v79 offset0:38 offset1:69
	v_cndmask_b32_e64 v53, v241, v49, s[44:45]
	v_add_u32_e32 v49, 0x400, v102
	v_add_u32_e32 v122, 0x400, v114
	ds_read2_b32 v[112:113], v49 offset0:38 offset1:69
	ds_read2_b32 v[114:115], v122 offset0:38 offset1:69
	s_waitcnt lgkmcnt(2)
	v_fmamk_f32 v48, v48, 0x3e000000, v108
	v_cndmask_b32_e64 v48, v241, v48, s[42:43]
	v_max3_f32 v47, v47, v48, v53
	s_waitcnt lgkmcnt(1)
	v_fmamk_f32 v38, v38, 0x3e000000, v112
	s_waitcnt lgkmcnt(0)
	v_fmamk_f32 v39, v39, 0x3e000000, v114
	v_cndmask_b32_e64 v38, v241, v38, s[46:47]
	v_cndmask_b32_e64 v103, v241, v39, s[48:49]
	v_max3_f32 v39, v47, v38, v103
	v_add_u32_e32 v47, 0x400, v116
	ds_read2_b32 v[116:117], v47 offset0:38 offset1:69
	v_add_u32_e32 v60, 0x400, v60
	ds_read2_b32 v[118:119], v60 offset0:38 offset1:69
	v_fmac_f32_e32 v109, 0x3e000000, v36
	v_cndmask_b32_e64 v101, v241, v109, s[42:43]
	s_waitcnt lgkmcnt(1)
	v_fmamk_f32 v40, v40, 0x3e000000, v116
	v_cndmask_b32_e64 v102, v241, v40, s[50:51]
	s_waitcnt lgkmcnt(0)
	v_fmamk_f32 v40, v41, 0x3e000000, v118
	v_fmac_f32_e32 v111, 0x3e000000, v37
	ds_read2_b32 v[108:109], v56 offset0:100 offset1:131
	v_cndmask_b32_e64 v106, v241, v40, s[52:53]
	v_cndmask_b32_e64 v40, v241, v111, s[44:45]
	ds_read2_b32 v[110:111], v63 offset0:100 offset1:131
	v_fmac_f32_e32 v105, 0x3e000000, v34
	v_fmac_f32_e32 v107, 0x3e000000, v35
	v_max3_f32 v39, v39, v102, v106
	v_cndmask_b32_e32 v105, v241, v105, vcc
	v_cndmask_b32_e64 v104, v241, v107, s[40:41]
	v_max3_f32 v34, v39, v105, v104
	v_fmac_f32_e32 v113, 0x3e000000, v30
	v_fmac_f32_e32 v115, 0x3e000000, v31
	v_max3_f32 v34, v34, v101, v40
	v_cndmask_b32_e64 v37, v241, v113, s[46:47]
	v_cndmask_b32_e64 v35, v241, v115, s[48:49]
	v_fmac_f32_e32 v119, 0x3e000000, v33
	s_waitcnt lgkmcnt(1)
	v_fmamk_f32 v33, v42, 0x3e000000, v108
	v_max3_f32 v31, v34, v37, v35
	v_cndmask_b32_e32 v34, v241, v33, vcc
	s_waitcnt lgkmcnt(0)
	v_fmamk_f32 v33, v43, 0x3e000000, v110
	ds_read2_b32 v[42:43], v79 offset0:100 offset1:131
	v_fmac_f32_e32 v117, 0x3e000000, v32
	ds_read2_b32 v[112:113], v81 offset0:100 offset1:131
	v_cndmask_b32_e64 v32, v241, v117, s[50:51]
	v_cndmask_b32_e64 v30, v241, v119, s[52:53]
	ds_read2_b32 v[114:115], v49 offset0:100 offset1:131
	ds_read2_b32 v[116:117], v122 offset0:100 offset1:131
	ds_read2_b32 v[118:119], v47 offset0:100 offset1:131
	ds_read2_b32 v[120:121], v60 offset0:100 offset1:131
	v_cndmask_b32_e64 v36, v241, v33, s[40:41]
	s_waitcnt lgkmcnt(5)
; __device__ __forceinline__ void mixC_mfma_unit(const bf16* Z, bf16* Yc, const float* rpb, LAS unsigned char* lds, int u, int S, int tid) {
;     ...
;     for (int t = 0; t < 16; ++t)
; #pragma unroll
;         for (int j = 0; j < 4; ++j) {
;             const int kr = rs + (t >> 1), kc = cbs + (t & 1) * 16 + 4 * q + j;
;             const bool valid = (kc >= cs) && (kc < cs + 16);
;             int dc = kc - qc + 15; dc = dc < 0 ? 0 : (dc > 30 ? 30 : dc);
;             const float sc = s[t][j] * 0.125f + rbp[(kr - qr + 7) * 31 + dc];
;             s[t][j] = valid ? sc : -1e30f; m = fmaxf(m, s[t][j]);
;         }
;     m = fmaxf(m, __shfl_xor(m, 16)); m = fmaxf(m, __shfl_xor(m, 32));
;     float l = 0.f;
; #pragma unroll
;     for (int t = 0; t < 16; ++t)
; #pragma unroll
;         for (int j = 0; j < 4; ++j) { const float pe = __expf(s[t][j] - m); s[t][j] = pe; l += pe; }
	v_fmamk_f32 v33, v44, 0x3e000000, v42
	v_max3_f32 v31, v31, v32, v30
	v_cndmask_b32_e64 v42, v241, v33, s[42:43]
	s_waitcnt lgkmcnt(4)
	v_fmamk_f32 v33, v45, 0x3e000000, v112
	v_max3_f32 v31, v31, v34, v36
	v_cndmask_b32_e64 v44, v241, v33, s[44:45]
	s_waitcnt lgkmcnt(3)
	v_fmamk_f32 v26, v26, 0x3e000000, v114
	s_waitcnt lgkmcnt(2)
	v_fmamk_f32 v27, v27, 0x3e000000, v116
	s_waitcnt lgkmcnt(1)
	v_fmamk_f32 v28, v28, 0x3e000000, v118
	v_max3_f32 v31, v31, v42, v44
	v_cndmask_b32_e64 v26, v241, v26, s[46:47]
	v_cndmask_b32_e64 v107, v241, v27, s[48:49]
	v_cndmask_b32_e64 v108, v241, v28, s[50:51]
	s_waitcnt lgkmcnt(0)
	v_fmamk_f32 v28, v29, 0x3e000000, v120
	v_max3_f32 v27, v31, v26, v107
	v_cndmask_b32_e64 v110, v241, v28, s[52:53]
	v_fmac_f32_e32 v109, 0x3e000000, v22
	v_fmac_f32_e32 v111, 0x3e000000, v23
	v_max3_f32 v27, v27, v108, v110
	v_cndmask_b32_e32 v109, v241, v109, vcc
	v_cndmask_b32_e64 v29, v241, v111, s[40:41]
	v_fmac_f32_e32 v43, 0x3e000000, v24
	v_fmac_f32_e32 v113, 0x3e000000, v25
	v_fmac_f32_e32 v115, 0x3e000000, v18
	v_max3_f32 v22, v27, v109, v29
	v_cndmask_b32_e64 v24, v241, v43, s[42:43]
	v_cndmask_b32_e64 v28, v241, v113, s[44:45]
	v_cndmask_b32_e64 v23, v241, v115, s[46:47]
	v_fmac_f32_e32 v117, 0x3e000000, v19
	v_fmac_f32_e32 v119, 0x3e000000, v20
	ds_read2_b32 v[112:113], v56 offset0:162 offset1:193
	ds_read2_b32 v[114:115], v63 offset0:162 offset1:193
	v_max3_f32 v25, v22, v24, v28
	v_cndmask_b32_e64 v22, v241, v117, s[48:49]
	v_cndmask_b32_e64 v19, v241, v119, s[50:51]
	v_fmac_f32_e32 v121, 0x3e000000, v21
	ds_read2_b32 v[116:117], v79 offset0:162 offset1:193
	ds_read2_b32 v[118:119], v81 offset0:162 offset1:193
	v_cndmask_b32_e64 v18, v241, v121, s[52:53]
	ds_read2_b32 v[120:121], v49 offset0:162 offset1:193
	ds_read2_b32 v[122:123], v122 offset0:162 offset1:193
	ds_read2_b32 v[124:125], v47 offset0:162 offset1:193
	ds_read2_b32 v[126:127], v60 offset0:162 offset1:193
	v_max3_f32 v25, v25, v23, v22
	s_waitcnt lgkmcnt(7)
	v_fmamk_f32 v14, v14, 0x3e000000, v112
	s_waitcnt lgkmcnt(6)
	v_fmamk_f32 v15, v15, 0x3e000000, v114
	v_max3_f32 v20, v25, v19, v18
	v_cndmask_b32_e32 v14, v241, v14, vcc
	v_cndmask_b32_e64 v15, v241, v15, s[40:41]
	s_waitcnt lgkmcnt(5)
	v_fmamk_f32 v16, v16, 0x3e000000, v116
	s_waitcnt lgkmcnt(4)
	v_fmamk_f32 v17, v17, 0x3e000000, v118
	v_max3_f32 v20, v20, v14, v15
	v_cndmask_b32_e64 v16, v241, v16, s[42:43]
	v_cndmask_b32_e64 v21, v241, v17, s[44:45]
	s_waitcnt lgkmcnt(3)
	v_fmamk_f32 v6, v6, 0x3e000000, v120
	s_waitcnt lgkmcnt(2)
	v_fmamk_f32 v7, v7, 0x3e000000, v122
	v_max3_f32 v17, v20, v16, v21
	v_cndmask_b32_e64 v6, v241, v6, s[46:47]
	v_cndmask_b32_e64 v7, v241, v7, s[48:49]
	s_waitcnt lgkmcnt(1)
	v_fmamk_f32 v8, v8, 0x3e000000, v124
	s_waitcnt lgkmcnt(0)
	v_fmamk_f32 v9, v9, 0x3e000000, v126
	v_max3_f32 v17, v17, v6, v7
	v_cndmask_b32_e64 v8, v241, v8, s[50:51]
	v_cndmask_b32_e64 v112, v241, v9, s[52:53]
	v_fmac_f32_e32 v113, 0x3e000000, v2
	v_fmac_f32_e32 v115, 0x3e000000, v3
	v_max3_f32 v17, v17, v8, v112
	v_cndmask_b32_e32 v113, v241, v113, vcc
	v_cndmask_b32_e64 v9, v241, v115, s[40:41]
	v_fmac_f32_e32 v117, 0x3e000000, v4
	v_fmac_f32_e32 v119, 0x3e000000, v5
	v_max3_f32 v2, v17, v113, v9
	v_cndmask_b32_e64 v111, v241, v117, s[42:43]
	v_cndmask_b32_e64 v5, v241, v119, s[44:45]
	v_fmac_f32_e32 v121, 0x3e000000, v10
	v_fmac_f32_e32 v123, 0x3e000000, v11
	v_max3_f32 v2, v2, v111, v5
	v_cndmask_b32_e64 v10, v241, v121, s[46:47]
	v_cndmask_b32_e64 v3, v241, v123, s[48:49]
	v_fmac_f32_e32 v125, 0x3e000000, v12
	v_fmac_f32_e32 v127, 0x3e000000, v13
	v_max3_f32 v11, v2, v10, v3
	v_cndmask_b32_e64 v4, v241, v125, s[50:51]
	v_cndmask_b32_e64 v2, v241, v127, s[52:53]
	v_max3_f32 v11, v11, v4, v2
	ds_bpermute_b32 v12, v69, v11
	s_waitcnt lgkmcnt(0)
	v_max_f32_e32 v12, v12, v12
	v_max_f32_e32 v11, v11, v12
	ds_bpermute_b32 v12, v82, v11
	s_waitcnt lgkmcnt(0)
	v_max_f32_e32 v12, v12, v12
	v_max_f32_e32 v13, v11, v12
	v_sub_f32_e32 v12, v97, v13
	v_mul_f32_e32 v12, 0x3fb8aa3b, v12
	v_exp_f32_e32 v60, v12
	v_sub_f32_e32 v12, v62, v13
	v_mul_f32_e32 v12, 0x3fb8aa3b, v12
	v_exp_f32_e32 v62, v12
	v_sub_f32_e32 v12, v64, v13
	v_mul_f32_e32 v12, 0x3fb8aa3b, v12
	v_exp_f32_e32 v63, v12
	v_sub_f32_e32 v12, v58, v13
	v_mul_f32_e32 v12, 0x3fb8aa3b, v12
	v_exp_f32_e32 v79, v12
	v_sub_f32_e32 v12, v59, v13
	v_mul_f32_e32 v12, 0x3fb8aa3b, v12
	v_exp_f32_e32 v81, v12
	v_sub_f32_e32 v12, v65, v13
	v_mul_f32_e32 v12, 0x3fb8aa3b, v12
	v_sub_f32_e32 v11, v96, v13
	v_exp_f32_e32 v96, v12
	v_sub_f32_e32 v12, v100, v13
	v_mul_f32_e32 v12, 0x3fb8aa3b, v12
	v_exp_f32_e32 v97, v12
	v_sub_f32_e32 v12, v99, v13
	v_mul_f32_e32 v12, 0x3fb8aa3b, v12
	v_exp_f32_e32 v47, v12
	v_sub_f32_e32 v12, v98, v13
	v_mul_f32_e32 v12, 0x3fb8aa3b, v12
	v_exp_f32_e32 v49, v12
	v_sub_f32_e32 v12, v54, v13
	v_mul_f32_e32 v12, 0x3fb8aa3b, v12
	v_exp_f32_e32 v54, v12
	v_sub_f32_e32 v12, v55, v13
	v_mul_f32_e32 v12, 0x3fb8aa3b, v12
	v_exp_f32_e32 v55, v12
	v_sub_f32_e32 v12, v61, v13
	v_mul_f32_e32 v12, 0x3fb8aa3b, v12
	v_exp_f32_e32 v58, v12
	v_sub_f32_e32 v12, v57, v13
	v_mul_f32_e32 v12, 0x3fb8aa3b, v12
	v_exp_f32_e32 v61, v12
	v_sub_f32_e32 v12, v51, v13
	v_mul_f32_e32 v12, 0x3fb8aa3b, v12
	v_exp_f32_e32 v64, v12
	v_sub_f32_e32 v12, v50, v13
	v_mul_f32_e32 v12, 0x3fb8aa3b, v12
	v_exp_f32_e32 v65, v12
	v_sub_f32_e32 v12, v46, v13
	v_mul_f32_e32 v12, 0x3fb8aa3b, v12
	v_exp_f32_e32 v39, v12
	v_sub_f32_e32 v12, v52, v13
	v_mul_f32_e32 v12, 0x3fb8aa3b, v12
	v_exp_f32_e32 v41, v12
	v_sub_f32_e32 v12, v48, v13
	v_mul_f32_e32 v12, 0x3fb8aa3b, v12
	v_exp_f32_e32 v46, v12
	v_sub_f32_e32 v12, v53, v13
	v_mul_f32_e32 v12, 0x3fb8aa3b, v12
; #define LAS __attribute__((address_space(3)))
; __device__ __forceinline__ void mixC_mfma_unit(const bf16* Z, bf16* Yc, const float* rpb, LAS unsigned char* lds, int u, int S, int tid) {
;     ...
;     for (int t = 0; t < 16; ++t)
; #pragma unroll
;         for (int j = 0; j < 4; ++j) { const float pe = __expf(s[t][j] - m); s[t][j] = pe; l += pe; }
;     l += __shfl_xor(l, 16); l += __shfl_xor(l, 32);
;     f32x4 o[4];
; #pragma unroll
;     for (int dt = 0; dt < 4; ++dt) o[dt] = (f32x4){0.f, 0.f, 0.f, 0.f};
;     LAS unsigned char* vb = lds + ((rs - rb) * 64 + cbs + 4 * q + ((lane >> 2) & 3)) * KPITCH + 8 * (lane & 3);
; #pragma unroll
;     for (int G = 0; G < 8; ++G) {
;         const bf16x8_t pb = packp(s[2 * G], s[2 * G + 1]);
	v_exp_f32_e32 v48, v12
	v_sub_f32_e32 v12, v38, v13
	v_mul_f32_e32 v12, 0x3fb8aa3b, v12
	v_exp_f32_e32 v51, v12
	v_sub_f32_e32 v12, v103, v13
	v_mul_f32_e32 v12, 0x3fb8aa3b, v12
	v_exp_f32_e32 v53, v12
	v_sub_f32_e32 v12, v102, v13
	v_mul_f32_e32 v12, 0x3fb8aa3b, v12
	v_exp_f32_e32 v57, v12
	v_sub_f32_e32 v12, v106, v13
	v_mul_f32_e32 v12, 0x3fb8aa3b, v12
	v_exp_f32_e32 v59, v12
	v_sub_f32_e32 v12, v105, v13
	v_mul_f32_e32 v12, 0x3fb8aa3b, v12
	v_exp_f32_e32 v31, v12
	v_sub_f32_e32 v12, v104, v13
	v_mul_f32_e32 v12, 0x3fb8aa3b, v12
	v_mul_f32_e32 v11, 0x3fb8aa3b, v11
	v_exp_f32_e32 v33, v12
	v_sub_f32_e32 v12, v101, v13
	v_exp_f32_e32 v56, v11
	v_mul_f32_e32 v12, 0x3fb8aa3b, v12
	v_exp_f32_e32 v38, v12
	v_sub_f32_e32 v12, v40, v13
	v_mul_f32_e32 v12, 0x3fb8aa3b, v12
	v_exp_f32_e32 v40, v12
	v_sub_f32_e32 v12, v37, v13
	v_add_f32_e32 v11, 0, v56
	v_mul_f32_e32 v12, 0x3fb8aa3b, v12
	v_add_f32_e32 v11, v60, v11
	v_exp_f32_e32 v43, v12
	v_sub_f32_e32 v12, v35, v13
	v_add_f32_e32 v11, v62, v11
	v_mul_f32_e32 v12, 0x3fb8aa3b, v12
	v_add_f32_e32 v11, v63, v11
	v_exp_f32_e32 v45, v12
	v_sub_f32_e32 v12, v32, v13
	v_add_f32_e32 v11, v79, v11
	v_mul_f32_e32 v12, 0x3fb8aa3b, v12
	v_add_f32_e32 v11, v81, v11
	v_exp_f32_e32 v50, v12
	v_sub_f32_e32 v12, v30, v13
	v_add_f32_e32 v11, v96, v11
	v_mul_f32_e32 v12, 0x3fb8aa3b, v12
	v_add_f32_e32 v11, v97, v11
	v_exp_f32_e32 v52, v12
	v_sub_f32_e32 v12, v34, v13
	v_add_f32_e32 v11, v47, v11
	v_mul_f32_e32 v12, 0x3fb8aa3b, v12
	v_add_f32_e32 v11, v49, v11
	v_exp_f32_e32 v25, v12
	v_sub_f32_e32 v12, v36, v13
	v_add_f32_e32 v11, v54, v11
	v_mul_f32_e32 v12, 0x3fb8aa3b, v12
	v_add_f32_e32 v11, v55, v11
	v_exp_f32_e32 v27, v12
	v_sub_f32_e32 v12, v42, v13
	v_add_f32_e32 v11, v58, v11
	v_mul_f32_e32 v12, 0x3fb8aa3b, v12
	v_add_f32_e32 v11, v61, v11
	v_exp_f32_e32 v30, v12
	v_sub_f32_e32 v12, v44, v13
	v_add_f32_e32 v11, v64, v11
	v_mul_f32_e32 v12, 0x3fb8aa3b, v12
	v_add_f32_e32 v11, v65, v11
	v_exp_f32_e32 v32, v12
	v_sub_f32_e32 v12, v26, v13
	v_add_f32_e32 v11, v39, v11
	v_mul_f32_e32 v12, 0x3fb8aa3b, v12
	v_add_f32_e32 v11, v41, v11
	v_exp_f32_e32 v35, v12
	v_sub_f32_e32 v12, v107, v13
	v_add_f32_e32 v11, v46, v11
	v_mul_f32_e32 v12, 0x3fb8aa3b, v12
	v_add_f32_e32 v11, v48, v11
	v_exp_f32_e32 v37, v12
	v_sub_f32_e32 v12, v108, v13
	v_add_f32_e32 v11, v51, v11
	v_mul_f32_e32 v12, 0x3fb8aa3b, v12
	v_add_f32_e32 v11, v53, v11
	v_exp_f32_e32 v42, v12
	v_sub_f32_e32 v12, v110, v13
	v_add_f32_e32 v11, v57, v11
	v_mul_f32_e32 v12, 0x3fb8aa3b, v12
	v_add_f32_e32 v11, v59, v11
	v_exp_f32_e32 v44, v12
	v_sub_f32_e32 v12, v109, v13
	v_add_f32_e32 v11, v31, v11
	v_mul_f32_e32 v12, 0x3fb8aa3b, v12
	v_add_f32_e32 v11, v33, v11
	v_exp_f32_e32 v17, v12
	v_sub_f32_e32 v12, v29, v13
	v_add_f32_e32 v11, v38, v11
	v_mul_f32_e32 v12, 0x3fb8aa3b, v12
	v_add_f32_e32 v11, v40, v11
	v_exp_f32_e32 v20, v12
	v_sub_f32_e32 v12, v24, v13
	v_add_f32_e32 v11, v43, v11
	v_mul_f32_e32 v12, 0x3fb8aa3b, v12
	v_add_f32_e32 v11, v45, v11
	v_exp_f32_e32 v24, v12
	v_sub_f32_e32 v12, v28, v13
	v_add_f32_e32 v11, v50, v11
	v_mul_f32_e32 v12, 0x3fb8aa3b, v12
	v_add_f32_e32 v11, v52, v11
	v_exp_f32_e32 v26, v12
	v_sub_f32_e32 v12, v23, v13
	v_add_f32_e32 v11, v25, v11
	v_mul_f32_e32 v12, 0x3fb8aa3b, v12
	v_add_f32_e32 v11, v27, v11
	v_exp_f32_e32 v28, v12
	v_sub_f32_e32 v12, v22, v13
	v_add_f32_e32 v11, v30, v11
	v_mul_f32_e32 v12, 0x3fb8aa3b, v12
	v_add_f32_e32 v11, v32, v11
	v_exp_f32_e32 v29, v12
	v_sub_f32_e32 v12, v19, v13
	v_add_f32_e32 v11, v35, v11
	v_mul_f32_e32 v12, 0x3fb8aa3b, v12
	v_add_f32_e32 v11, v37, v11
	v_exp_f32_e32 v34, v12
	v_sub_f32_e32 v12, v18, v13
	v_add_f32_e32 v11, v42, v11
	v_mul_f32_e32 v12, 0x3fb8aa3b, v12
	v_add_f32_e32 v11, v44, v11
	v_exp_f32_e32 v36, v12
	v_sub_f32_e32 v12, v14, v13
	v_add_f32_e32 v11, v17, v11
	v_mul_f32_e32 v12, 0x3fb8aa3b, v12
	v_add_f32_e32 v11, v20, v11
	v_exp_f32_e32 v14, v12
	v_sub_f32_e32 v12, v15, v13
	v_add_f32_e32 v11, v24, v11
	v_mul_f32_e32 v12, 0x3fb8aa3b, v12
	v_add_f32_e32 v11, v26, v11
	v_exp_f32_e32 v15, v12
	v_sub_f32_e32 v12, v16, v13
	v_add_f32_e32 v11, v28, v11
	v_mul_f32_e32 v12, 0x3fb8aa3b, v12
	v_add_f32_e32 v11, v29, v11
	v_exp_f32_e32 v16, v12
	v_sub_f32_e32 v12, v21, v13
	v_sub_f32_e32 v7, v7, v13
	v_add_f32_e32 v11, v34, v11
	v_mul_f32_e32 v12, 0x3fb8aa3b, v12
	v_sub_f32_e32 v6, v6, v13
	v_mul_f32_e32 v7, 0x3fb8aa3b, v7
	v_add_f32_e32 v11, v36, v11
	v_exp_f32_e32 v18, v12
	v_mul_f32_e32 v6, 0x3fb8aa3b, v6
	v_exp_f32_e32 v21, v7
	v_sub_f32_e32 v7, v8, v13
	v_add_f32_e32 v11, v14, v11
	v_exp_f32_e32 v19, v6
	v_mul_f32_e32 v7, 0x3fb8aa3b, v7
	v_add_f32_e32 v11, v15, v11
	v_exp_f32_e32 v22, v7
	v_sub_f32_e32 v7, v112, v13
	v_add_f32_e32 v11, v16, v11
	v_mul_f32_e32 v7, 0x3fb8aa3b, v7
	v_add_f32_e32 v11, v18, v11
	v_exp_f32_e32 v23, v7
	v_add_f32_e32 v6, v19, v11
	v_add_f32_e32 v6, v21, v6
	v_add_f32_e32 v6, v22, v6
	v_add_f32_e32 v7, v23, v6
	v_sub_f32_e32 v6, v113, v13
	v_mul_f32_e32 v6, 0x3fb8aa3b, v6
	v_exp_f32_e32 v6, v6
	v_sub_f32_e32 v5, v5, v13
	v_mul_f32_e32 v5, 0x3fb8aa3b, v5
	v_sub_f32_e32 v10, v10, v13
	v_add_f32_e32 v8, v6, v7
	v_sub_f32_e32 v7, v9, v13
	v_mul_f32_e32 v7, 0x3fb8aa3b, v7
	v_exp_f32_e32 v7, v7
	v_mul_f32_e32 v10, 0x3fb8aa3b, v10
	v_sub_f32_e32 v3, v3, v13
	v_exp_f32_e32 v10, v10
	v_add_f32_e32 v9, v7, v8
	v_sub_f32_e32 v8, v111, v13
	v_mul_f32_e32 v8, 0x3fb8aa3b, v8
	v_exp_f32_e32 v8, v8
	v_mul_f32_e32 v3, 0x3fb8aa3b, v3
	v_sub_f32_e32 v4, v4, v13
	v_mul_f32_e32 v4, 0x3fb8aa3b, v4
	v_add_f32_e32 v11, v8, v9
	v_exp_f32_e32 v9, v5
	v_sub_f32_e32 v2, v2, v13
	v_exp_f32_e32 v12, v4
	v_mul_f32_e32 v2, 0x3fb8aa3b, v2
	v_add_f32_e32 v5, v9, v11
	v_exp_f32_e32 v11, v3
	v_exp_f32_e32 v13, v2
	v_add_f32_e32 v5, v10, v5
	v_cvt_pk_bf16_f32 v98, v56, v60
	v_add_f32_e32 v3, v11, v5
	v_add_f32_e32 v3, v12, v3
	v_add_f32_e32 v2, v13, v3
	ds_bpermute_b32 v3, v69, v2
	v_cvt_pk_bf16_f32 v99, v62, v63
	v_cvt_pk_bf16_f32 v100, v79, v81
	v_cvt_pk_bf16_f32 v101, v96, v97
	v_add_u32_e32 v81, 2, v88
	s_waitcnt lgkmcnt(0)
; #define LAS __attribute__((address_space(3)))
; __device__ __forceinline__ s16x4_t trread(LAS unsigned char* p) { return __builtin_amdgcn_ds_read_tr16_b64_v4i16((LAS s16x4_t*)p); }
; __device__ __forceinline__ bf16x8_t cat4(s16x4_t a, s16x4_t b) { return (bf16x8_t){a[0], a[1], a[2], a[3], b[0], b[1], b[2], b[3]}; }
; __device__ __forceinline__ void mixC_mfma_unit(const bf16* Z, bf16* Yc, const float* rpb, LAS unsigned char* lds, int u, int S, int tid) {
;     ...
;     f32x4 o[4];
; #pragma unroll
;     for (int dt = 0; dt < 4; ++dt) o[dt] = (f32x4){0.f, 0.f, 0.f, 0.f};
;     LAS unsigned char* vb = lds + ((rs - rb) * 64 + cbs + 4 * q + ((lane >> 2) & 3)) * KPITCH + 8 * (lane & 3);
; #pragma unroll
;     for (int G = 0; G < 8; ++G) {
;         const bf16x8_t pb = packp(s[2 * G], s[2 * G + 1]);
; #pragma unroll
;         for (int dt = 0; dt < 4; ++dt) {
;             const s16x4_t lo = trread(vb + (64 * G) * KPITCH + dt * 32), hi = trread(vb + (64 * G + 16) * KPITCH + dt * 32);
;             o[dt] = __builtin_amdgcn_mfma_f32_16x16x32_bf16(cat4(lo, hi), pb, o[dt], 0, 0, 0);
;         }
;     }
	v_add_f32_e32 v4, v2, v3
	v_subrev_u32_e32 v2, s2, v95
	v_lshl_add_u32 v2, v2, 6, v1
	v_mad_u64_u32 v[2:3], s[16:17], v2, s67, v[68:69]
	ds_read_b64_tr_b16 v[104:105], v2 offset:2304
	ds_read_b64_tr_b16 v[102:103], v2
	ds_read_b64_tr_b16 v[106:107], v2 offset:32
	ds_read_b64_tr_b16 v[108:109], v2 offset:2336
	ds_read_b64_tr_b16 v[110:111], v2 offset:64
	ds_read_b64_tr_b16 v[112:113], v2 offset:2368
	ds_read_b64_tr_b16 v[114:115], v2 offset:96
	ds_read_b64_tr_b16 v[116:117], v2 offset:2400
	s_waitcnt lgkmcnt(6)
	v_mfma_f32_16x16x32_bf16 v[102:105], v[102:105], v[98:101], 0
	v_add_u32_e32 v3, 0x10500, v2
	ds_bpermute_b32 v5, v82, v4
	v_cmp_lt_i32_e64 s[54:55], 3, v81
	s_waitcnt lgkmcnt(5)
	v_mfma_f32_16x16x32_bf16 v[106:109], v[106:109], v[98:101], 0
	s_waitcnt lgkmcnt(3)
	v_mfma_f32_16x16x32_bf16 v[110:113], v[110:113], v[98:101], 0
	s_waitcnt lgkmcnt(1)
	v_mfma_f32_16x16x32_bf16 v[96:99], v[114:117], v[98:101], 0
	v_cvt_pk_bf16_f32 v114, v47, v49
	v_cvt_pk_bf16_f32 v115, v54, v55
	v_cvt_pk_bf16_f32 v116, v58, v61
	v_cvt_pk_bf16_f32 v117, v64, v65
	ds_read_b64_tr_b16 v[62:63], v2 offset:11520
	ds_read_b64_tr_b16 v[60:61], v2 offset:9216
	ds_read_b64_tr_b16 v[100:101], v2 offset:9248
	s_waitcnt lgkmcnt(1)
	v_mfma_f32_16x16x32_bf16 v[60:63], v[60:63], v[114:117], v[102:105]
	s_nop 2
	ds_read_b64_tr_b16 v[102:103], v2 offset:11552
	s_waitcnt lgkmcnt(0)
	v_mfma_f32_16x16x32_bf16 v[100:103], v[100:103], v[114:117], v[106:109]
	ds_read_b64_tr_b16 v[104:105], v2 offset:9280
	s_nop 1
	ds_read_b64_tr_b16 v[106:107], v2 offset:11584
	s_waitcnt lgkmcnt(0)
	v_mfma_f32_16x16x32_bf16 v[104:107], v[104:107], v[114:117], v[110:113]
	ds_read_b64_tr_b16 v[108:109], v2 offset:9312
	s_nop 1
	ds_read_b64_tr_b16 v[110:111], v2 offset:11616
	v_cvt_pk_bf16_f32 v54, v39, v41
	v_cvt_pk_bf16_f32 v55, v46, v48
	v_cvt_pk_bf16_f32 v56, v51, v53
	v_cvt_pk_bf16_f32 v57, v57, v59
	ds_read_b64_tr_b16 v[48:49], v2 offset:20736
	ds_read_b64_tr_b16 v[46:47], v2 offset:18432
	ds_read_b64_tr_b16 v[58:59], v2 offset:18464
	s_waitcnt lgkmcnt(1)
	v_mfma_f32_16x16x32_bf16 v[46:49], v[46:49], v[54:57], v[60:63]
	s_nop 2
	ds_read_b64_tr_b16 v[60:61], v2 offset:20768
	ds_read_b64_tr_b16 v[62:63], v2 offset:18496
	ds_read_b64_tr_b16 v[64:65], v2 offset:20800
	s_waitcnt lgkmcnt(2)
	v_mfma_f32_16x16x32_bf16 v[58:61], v[58:61], v[54:57], v[100:103]
	s_nop 2
	ds_read_b64_tr_b16 v[100:101], v2 offset:18528
	ds_read_b64_tr_b16 v[102:103], v2 offset:20832
	v_mfma_f32_16x16x32_bf16 v[96:99], v[108:111], v[114:117], v[96:99]
	s_waitcnt lgkmcnt(2)
	v_mfma_f32_16x16x32_bf16 v[62:65], v[62:65], v[54:57], v[104:107]
	s_waitcnt lgkmcnt(0)
	v_mfma_f32_16x16x32_bf16 v[54:57], v[100:103], v[54:57], v[96:99]
	v_cvt_pk_bf16_f32 v96, v31, v33
	v_cvt_pk_bf16_f32 v97, v38, v40
	v_cvt_pk_bf16_f32 v98, v43, v45
	v_cvt_pk_bf16_f32 v99, v50, v52
	ds_read_b64_tr_b16 v[40:41], v2 offset:29952
	ds_read_b64_tr_b16 v[38:39], v2 offset:27648
	ds_read_b64_tr_b16 v[50:51], v2 offset:27680
	ds_read_b64_tr_b16 v[52:53], v2 offset:29984
	s_waitcnt lgkmcnt(2)
	v_mfma_f32_16x16x32_bf16 v[38:41], v[38:41], v[96:99], v[46:49]
	s_waitcnt lgkmcnt(0)
	v_mfma_f32_16x16x32_bf16 v[46:49], v[50:53], v[96:99], v[58:61]
	ds_read_b64_tr_b16 v[50:51], v2 offset:27712
	ds_read_b64_tr_b16 v[52:53], v2 offset:30016
	s_nop 0
	ds_read_b64_tr_b16 v[58:59], v2 offset:27744
	ds_read_b64_tr_b16 v[60:61], v2 offset:30048
	s_waitcnt lgkmcnt(0)
	v_mfma_f32_16x16x32_bf16 v[54:57], v[58:61], v[96:99], v[54:57]
	v_cvt_pk_bf16_f32 v58, v25, v27
	v_cvt_pk_bf16_f32 v59, v30, v32
	v_cvt_pk_bf16_f32 v60, v35, v37
	v_cvt_pk_bf16_f32 v61, v42, v44
	ds_read_b64_tr_b16 v[32:33], v2 offset:39168
	ds_read_b64_tr_b16 v[30:31], v2 offset:36864
	ds_read_b64_tr_b16 v[42:43], v2 offset:36896
	ds_read_b64_tr_b16 v[44:45], v2 offset:39200
	s_waitcnt lgkmcnt(2)
	v_mfma_f32_16x16x32_bf16 v[30:33], v[30:33], v[58:61], v[38:41]
	s_waitcnt lgkmcnt(0)
	v_mfma_f32_16x16x32_bf16 v[38:41], v[42:45], v[58:61], v[46:49]
	ds_read_b64_tr_b16 v[42:43], v2 offset:36928
	ds_read_b64_tr_b16 v[44:45], v2 offset:39232
	s_nop 0
	ds_read_b64_tr_b16 v[46:47], v2 offset:36960
	ds_read_b64_tr_b16 v[48:49], v2 offset:39264
	v_mfma_f32_16x16x32_bf16 v[50:53], v[50:53], v[96:99], v[62:65]
	s_waitcnt lgkmcnt(2)
	v_mfma_f32_16x16x32_bf16 v[42:45], v[42:45], v[58:61], v[50:53]
	v_cvt_pk_bf16_f32 v50, v17, v20
	v_cvt_pk_bf16_f32 v51, v24, v26
	v_cvt_pk_bf16_f32 v52, v28, v29
	v_cvt_pk_bf16_f32 v53, v34, v36
	ds_read_b64_tr_b16 v[26:27], v2 offset:48384
	ds_read_b64_tr_b16 v[24:25], v2 offset:46080
	ds_read_b64_tr_b16 v[28:29], v2 offset:46112
	s_waitcnt lgkmcnt(1)
	s_nop 1
	v_mfma_f32_16x16x32_bf16 v[24:27], v[24:27], v[50:53], v[30:33]
	s_nop 2
	ds_read_b64_tr_b16 v[30:31], v2 offset:48416
	ds_read_b64_tr_b16 v[32:33], v2 offset:46144
	ds_read_b64_tr_b16 v[34:35], v2 offset:48448
	s_waitcnt lgkmcnt(2)
	v_mfma_f32_16x16x32_bf16 v[28:31], v[28:31], v[50:53], v[38:41]
	ds_read_b64_tr_b16 v[36:37], v2 offset:46176
	s_nop 1
	ds_read_b64_tr_b16 v[38:39], v2 offset:48480
	v_cvt_pk_bf16_f32 v14, v14, v15
	v_cvt_pk_bf16_f32 v15, v16, v18
	v_cvt_pk_bf16_f32 v16, v19, v21
	v_cvt_pk_bf16_f32 v17, v22, v23
	ds_read_b64_tr_b16 v[20:21], v2 offset:57600
	ds_read_b64_tr_b16 v[18:19], v2 offset:55296
	ds_read_b64_tr_b16 v[22:23], v2 offset:55328
	s_waitcnt lgkmcnt(1)
	v_mfma_f32_16x16x32_bf16 v[18:21], v[18:21], v[14:17], v[24:27]
	s_nop 2
	ds_read_b64_tr_b16 v[24:25], v2 offset:57632
	s_waitcnt lgkmcnt(0)
	v_mfma_f32_16x16x32_bf16 v[22:25], v[22:25], v[14:17], v[28:31]
	ds_read_b64_tr_b16 v[26:27], v2 offset:55360
	s_nop 1
	ds_read_b64_tr_b16 v[28:29], v2 offset:57664
	v_mfma_f32_16x16x32_bf16 v[32:35], v[32:35], v[50:53], v[42:45]
	v_mfma_f32_16x16x32_bf16 v[46:49], v[46:49], v[58:61], v[54:57]
	s_waitcnt lgkmcnt(0)
; __device__ __forceinline__ unsigned cvt_pk_bf16(float lo, float hi) { unsigned r; asm volatile("v_cvt_pk_bf16_f32 %0, %1, %2" : "=v"(r) : "v"(lo), "v"(hi)); return r; }
; __device__ __forceinline__ void mixC_mfma_unit(const bf16* Z, bf16* Yc, const float* rpb, LAS unsigned char* lds, int u, int S, int tid) {
;     ...
;     for (int qt = 0; qt < 2; ++qt) {
;     const int qr = 4 * np + 2 * qt + (w >> 2), cb = w & 3, qc = cb * 16 + n;
;     int rs = qr - 4; rs = rs < 0 ? 0 : (rs > rows - 8 ? rows - 8 : rs);
;     int cbs = cb * 16 - 8; cbs = cbs < 0 ? 0 : (cbs > 32 ? 32 : cbs);
;     int cs = qc - 8; cs = cs < 0 ? 0 : (cs > 48 ? 48 : cs);
;     const int tokc = seq0 + qr * 64 + qc;
;     const bf16* qp = Z + (size_t)tokc * NZ + 6144 + h * 64;
;     const bf16x8_t qf0 = *(const bf16x8_t*)(qp + 8 * q), qf1 = *(const bf16x8_t*)(qp + 32 + 8 * q);
;     f32x4 s[16];
; #pragma unroll
;     for (int hf = 0; hf < 2; ++hf) {
;         bf16x8_t kf[8][2];
; #pragma unroll
;         for (int tt = 0; tt < 8; ++tt) { const int t = 8 * hf + tt;
;             const bf16* kp = zk + (size_t)((rs + (t >> 1)) * 64 + cbs + (t & 1) * 16 + n) * NZ + 8 * q;
;             kf[tt][0] = *(const bf16x8_t*)kp; kf[tt][1] = *(const bf16x8_t*)(kp + 32); }
; #pragma unroll
;         for (int tt = 0; tt < 8; ++tt) {
;             f32x4 a = {0.f, 0.f, 0.f, 0.f};
;             a = __builtin_amdgcn_mfma_f32_16x16x32_bf16(kf[tt][0], qf0, a, 0, 0, 0);
;             s[8 * hf + tt] = __builtin_amdgcn_mfma_f32_16x16x32_bf16(kf[tt][1], qf1, a, 0, 0, 0);
;         }
;     ...
;     for (int G = 0; G < 8; ++G) {
;         const bf16x8_t pb = packp(s[2 * G], s[2 * G + 1]);
; #pragma unroll
;         for (int dt = 0; dt < 4; ++dt) {
;             const s16x4_t lo = trread(vb + (64 * G) * KPITCH + dt * 32), hi = trread(vb + (64 * G + 16) * KPITCH + dt * 32);
;             o[dt] = __builtin_amdgcn_mfma_f32_16x16x32_bf16(cat4(lo, hi), pb, o[dt], 0, 0, 0);
;         }
;     }
;     const float inv = __builtin_amdgcn_rcpf(l);
;     bf16* yp = Yc + (size_t)tokc * 512 + h * 64;
; #pragma unroll
;     for (int dt = 0; dt < 4; ++dt) { uint2 wv; wv.x = pg8::cvt_pk_bf16(o[dt][0] * inv, o[dt][1] * inv); wv.y = pg8::cvt_pk_bf16(o[dt][2] * inv, o[dt][3] * inv);
;         *(uint2*)(yp + dt * 16 + 4 * q) = wv; }
	v_mfma_f32_16x16x32_bf16 v[26:29], v[26:29], v[14:17], v[32:35]
	ds_read_b64_tr_b16 v[30:31], v2 offset:55392
	s_nop 3
	ds_read_b64_tr_b16 v[32:33], v2 offset:57696
	v_cvt_pk_bf16_f32 v6, v6, v7
	v_cvt_pk_bf16_f32 v7, v8, v9
	v_mfma_f32_16x16x32_bf16 v[36:39], v[36:39], v[50:53], v[46:49]
	v_cvt_pk_bf16_f32 v8, v10, v11
	v_cvt_pk_bf16_f32 v9, v12, v13
	s_waitcnt lgkmcnt(0)
	v_mfma_f32_16x16x32_bf16 v[14:17], v[30:33], v[14:17], v[36:39]
	ds_read_b64_tr_b16 v[12:13], v3
	ds_read_b64_tr_b16 v[10:11], v2 offset:64512
	ds_read_b64_tr_b16 v[30:31], v2 offset:64544
	v_add_u32_e32 v3, 0x10520, v2
	ds_read_b64_tr_b16 v[32:33], v3
	v_add_u32_e32 v3, 0x10540, v2
	s_waitcnt lgkmcnt(2)
	v_mfma_f32_16x16x32_bf16 v[10:13], v[10:13], v[6:9], v[18:21]
	s_waitcnt lgkmcnt(0)
	v_mfma_f32_16x16x32_bf16 v[18:21], v[30:33], v[6:9], v[22:25]
	s_nop 2
	ds_read_b64_tr_b16 v[22:23], v2 offset:64576
	ds_read_b64_tr_b16 v[24:25], v3
	s_waitcnt lgkmcnt(0)
	v_mfma_f32_16x16x32_bf16 v[22:25], v[22:25], v[6:9], v[26:29]
	s_nop 2
	ds_read_b64_tr_b16 v[26:27], v2 offset:64608
	v_add_u32_e32 v2, 0x10560, v2
	ds_read_b64_tr_b16 v[28:29], v2
	v_add_f32_e32 v2, v4, v5
	s_waitcnt lgkmcnt(0)
	v_mfma_f32_16x16x32_bf16 v[6:9], v[26:29], v[6:9], v[14:17]
	s_nop 2
	v_rcp_f32_e32 v14, v2
	v_lshlrev_b64 v[2:3], 10, v[76:77]
	v_lshl_add_u64 v[2:3], v[66:67], 0, v[2:3]
	v_lshl_add_u32 v76, v81, 6, v89
	v_mul_f32_e32 v4, v14, v10
	v_mul_f32_e32 v5, v14, v11
	v_cvt_pk_bf16_f32 v4, v4, v5
	v_mul_f32_e32 v5, v14, v12
	v_mul_f32_e32 v10, v14, v13
	v_cvt_pk_bf16_f32 v5, v5, v10
	v_lshrrev_b32_e32 v218, 4, v231
	v_lshl_or_b32 v218, v231, 4, v218
	v_and_b32_e32 v218, 0x33, v218
	v_and_or_b32 v218, v231, 12, v218
	v_lshlrev_b32_e32 v218, 2, v218
	ds_bpermute_b32 v220, v218, v2
	ds_bpermute_b32 v221, v218, v3
	ds_bpermute_b32 v4, v218, v4
	ds_bpermute_b32 v5, v218, v5
	s_waitcnt lgkmcnt(0)
	global_store_dwordx2 v[220:221], v[4:5], off
	v_mul_f32_e32 v4, v14, v18
	v_mul_f32_e32 v5, v14, v19
	v_cvt_pk_bf16_f32 v4, v4, v5
	v_mul_f32_e32 v5, v14, v20
	v_mul_f32_e32 v10, v14, v21
	v_cvt_pk_bf16_f32 v5, v5, v10
	ds_bpermute_b32 v4, v218, v4
	ds_bpermute_b32 v5, v218, v5
	s_waitcnt lgkmcnt(0)
	global_store_dwordx2 v[220:221], v[4:5], off offset:32
	v_mul_f32_e32 v4, v14, v22
	v_mul_f32_e32 v5, v14, v23
	v_cvt_pk_bf16_f32 v4, v4, v5
	v_mul_f32_e32 v5, v14, v24
	v_mul_f32_e32 v10, v14, v25
	v_cvt_pk_bf16_f32 v5, v5, v10
	ds_bpermute_b32 v4, v218, v4
	ds_bpermute_b32 v5, v218, v5
	s_waitcnt lgkmcnt(0)
	global_store_dwordx2 v[220:221], v[4:5], off offset:64
	v_mul_f32_e32 v4, v14, v6
	v_mul_f32_e32 v5, v14, v7
	v_cvt_pk_bf16_f32 v4, v4, v5
	v_mul_f32_e32 v5, v14, v8
	v_mul_f32_e32 v6, v14, v9
	v_cvt_pk_bf16_f32 v5, v5, v6
	ds_bpermute_b32 v4, v218, v4
	ds_bpermute_b32 v5, v218, v5
	s_waitcnt lgkmcnt(0)
	global_store_dwordx2 v[220:221], v[4:5], off offset:96
	v_add_u32_e32 v2, -2, v88
	v_min_i32_e32 v2, s21, v2
	v_cndmask_b32_e64 v79, 0, v2, s[54:55]
	v_mad_i64_i32 v[2:3], s[16:17], v76, s66, v[74:75]
	v_lshl_add_u64 v[2:3], v[2:3], 0, s[70:71]
	v_lshl_add_u64 v[2:3], v[2:3], 0, v[72:73]
	v_lshl_add_u64 v[6:7], v[2:3], 0, s[24:25]
	v_add_co_u32_e64 v2, s[54:55], s20, v2
	v_lshlrev_b32_e32 v95, 6, v79
	s_nop 0
	v_addc_co_u32_e64 v3, s[54:55], 0, v3, s[54:55]
	s_nop 0
	v_add_u32_e32 v6, v95, v83
	v_mad_i64_i32 v[14:15], s[16:17], v6, s66, v[70:71]
	s_nop 0
	v_add_u32_e32 v18, v95, v84
	v_mad_i64_i32 v[22:23], s[16:17], v18, s66, v[70:71]
	s_nop 0
	v_add_u32_e32 v34, 64, v95
	v_add_u32_e32 v26, v34, v83
	v_mad_i64_i32 v[30:31], s[16:17], v26, s66, v[70:71]
	s_nop 0
	v_add_u32_e32 v34, v34, v84
	v_mad_i64_i32 v[38:39], s[16:17], v34, s66, v[70:71]
	s_nop 0
	v_add_u32_e32 v50, 0x80, v95
	v_add_u32_e32 v42, v50, v83
	v_mad_i64_i32 v[46:47], s[16:17], v42, s66, v[70:71]
	s_nop 0
	v_add_u32_e32 v50, v50, v84
	v_mad_i64_i32 v[50:51], s[16:17], v50, s66, v[70:71]
	v_add_u32_e32 v52, 0xc0, v95
	v_add_u32_e32 v50, v52, v83
	v_mad_i64_i32 v[50:51], s[16:17], v50, s66, v[70:71]
	v_add_u32_e32 v50, v52, v84
	v_mad_i64_i32 v[50:51], s[16:17], v50, s66, v[70:71]
	s_waitcnt vmcnt(4)
	v_mfma_f32_16x16x32_bf16 v[6:9], v[128:131], v[222:225], 0
	v_ashrrev_i32_e32 v77, 31, v76
	v_mfma_f32_16x16x32_bf16 v[62:65], v[132:135], v[176:179], v[6:9]
	v_mfma_f32_16x16x32_bf16 v[6:9], v[136:139], v[222:225], 0
	v_mfma_f32_16x16x32_bf16 v[50:53], v[140:143], v[176:179], v[6:9]
	v_mfma_f32_16x16x32_bf16 v[6:9], v[144:147], v[222:225], 0
	v_mfma_f32_16x16x32_bf16 v[54:57], v[148:151], v[176:179], v[6:9]
	v_mfma_f32_16x16x32_bf16 v[6:9], v[152:155], v[222:225], 0
	v_mfma_f32_16x16x32_bf16 v[58:61], v[156:159], v[176:179], v[6:9]
	v_mfma_f32_16x16x32_bf16 v[6:9], v[160:163], v[222:225], 0
	v_mfma_f32_16x16x32_bf16 v[46:49], v[164:167], v[176:179], v[6:9]
	v_mfma_f32_16x16x32_bf16 v[6:9], v[168:171], v[222:225], 0
	v_mfma_f32_16x16x32_bf16 v[34:37], v[172:175], v[176:179], v[6:9]
	v_mfma_f32_16x16x32_bf16 v[6:9], v[180:183], v[222:225], 0
	v_mfma_f32_16x16x32_bf16 v[38:41], v[184:187], v[176:179], v[6:9]
	v_mfma_f32_16x16x32_bf16 v[6:9], v[188:191], v[222:225], 0
	v_mfma_f32_16x16x32_bf16 v[30:33], v[192:195], v[176:179], v[6:9]
	v_add_u32_e32 v14, 0x100, v95
	v_add_u32_e32 v18, 0x140, v95
	v_add_u32_e32 v44, 0x180, v95
	v_add_u32_e32 v45, 0x1c0, v95
	v_add_u32_e32 v6, v14, v83
	v_add_u32_e32 v14, v14, v84
	v_add_u32_e32 v19, v18, v83
	v_add_u32_e32 v22, v18, v84
	v_add_u32_e32 v26, v44, v83
	v_add_u32_e32 v44, v44, v84
	v_add_u32_e32 v23, v45, v83
	v_add_u32_e32 v45, v45, v84
	v_mad_i64_i32 v[42:43], s[16:17], v6, s66, v[70:71]
	v_mad_i64_i32 v[88:89], s[16:17], v14, s66, v[70:71]
	v_mad_i64_i32 v[112:113], s[16:17], v19, s66, v[70:71]
	v_mad_i64_i32 v[114:115], s[16:17], v22, s66, v[70:71]
	v_mad_i64_i32 v[116:117], s[16:17], v26, s66, v[70:71]
	v_mad_i64_i32 v[118:119], s[16:17], v44, s66, v[70:71]
	v_mad_i64_i32 v[120:121], s[16:17], v23, s66, v[70:71]
	v_mad_i64_i32 v[70:71], s[16:17], v45, s66, v[70:71]
	global_load_dwordx4 v[6:9], v[42:43], off
	global_load_dwordx4 v[14:17], v[88:89], off
	global_load_dwordx4 v[18:21], v[112:113], off
	global_load_dwordx4 v[72:75], v[114:115], off
	global_load_dwordx4 v[96:99], v[116:117], off
	global_load_dwordx4 v[100:103], v[118:119], off
	global_load_dwordx4 v[104:107], v[120:121], off
	global_load_dwordx4 v[108:111], v[70:71], off
	global_load_dwordx4 v[180:183], v[42:43], off offset:64
	global_load_dwordx4 v[184:187], v[88:89], off offset:64
	global_load_dwordx4 v[188:191], v[112:113], off offset:64
	global_load_dwordx4 v[192:195], v[114:115], off offset:64
	global_load_dwordx4 v[202:205], v[116:117], off offset:64
	global_load_dwordx4 v[206:209], v[118:119], off offset:64
	global_load_dwordx4 v[210:213], v[120:121], off offset:64
	global_load_dwordx4 v[214:217], v[70:71], off offset:64
	s_waitcnt vmcnt(15)
; #define LAS __attribute__((address_space(3)))
; __device__ __forceinline__ void mixC_mfma_unit(const bf16* Z, bf16* Yc, const float* rpb, LAS unsigned char* lds, int u, int S, int tid) {
;     ...
;         for (int tt = 0; tt < 8; ++tt) {
;             f32x4 a = {0.f, 0.f, 0.f, 0.f};
;             a = __builtin_amdgcn_mfma_f32_16x16x32_bf16(kf[tt][0], qf0, a, 0, 0, 0);
;             s[8 * hf + tt] = __builtin_amdgcn_mfma_f32_16x16x32_bf16(kf[tt][1], qf1, a, 0, 0, 0);
;         }
;         __builtin_amdgcn_sched_barrier(0);
;     }
;     const LAS float* rbp = (const LAS float*)(lds + C_ROWS * KPITCH);
;     float m = -1e30f;
; #pragma unroll
;     for (int t = 0; t < 16; ++t)
; #pragma unroll
;         for (int j = 0; j < 4; ++j) {
;             const int kr = rs + (t >> 1), kc = cbs + (t & 1) * 16 + 4 * q + j;
;             const bool valid = (kc >= cs) && (kc < cs + 16);
;             int dc = kc - qc + 15; dc = dc < 0 ? 0 : (dc > 30 ? 30 : dc);
;             const float sc = s[t][j] * 0.125f + rbp[(kr - qr + 7) * 31 + dc];
;             s[t][j] = valid ? sc : -1e30f; m = fmaxf(m, s[t][j]);
;         }
	v_mfma_f32_16x16x32_bf16 v[6:9], v[6:9], v[222:225], 0
	s_waitcnt vmcnt(14)
	v_mfma_f32_16x16x32_bf16 v[14:17], v[14:17], v[222:225], 0
	s_waitcnt vmcnt(13)
	v_mfma_f32_16x16x32_bf16 v[18:21], v[18:21], v[222:225], 0
	s_waitcnt vmcnt(12)
	v_mfma_f32_16x16x32_bf16 v[72:75], v[72:75], v[222:225], 0
	s_waitcnt vmcnt(11)
	v_mfma_f32_16x16x32_bf16 v[96:99], v[96:99], v[222:225], 0
	s_waitcnt vmcnt(10)
	v_mfma_f32_16x16x32_bf16 v[100:103], v[100:103], v[222:225], 0
	s_waitcnt vmcnt(9)
	v_mfma_f32_16x16x32_bf16 v[104:107], v[104:107], v[222:225], 0
	s_waitcnt vmcnt(8)
	v_mfma_f32_16x16x32_bf16 v[108:111], v[108:111], v[222:225], 0
	s_waitcnt vmcnt(7)
	v_mfma_f32_16x16x32_bf16 v[42:45], v[180:183], v[176:179], v[6:9]
	s_waitcnt vmcnt(6)
	v_mfma_f32_16x16x32_bf16 v[26:29], v[184:187], v[176:179], v[14:17]
	s_waitcnt vmcnt(5)
	v_mfma_f32_16x16x32_bf16 v[22:25], v[188:191], v[176:179], v[18:21]
	s_waitcnt vmcnt(4)
	v_mfma_f32_16x16x32_bf16 v[18:21], v[192:195], v[176:179], v[72:75]
	s_waitcnt vmcnt(3)
	v_mfma_f32_16x16x32_bf16 v[14:17], v[202:205], v[176:179], v[96:99]
	s_waitcnt vmcnt(2)
	v_mfma_f32_16x16x32_bf16 v[6:9], v[206:209], v[176:179], v[100:103]
	s_waitcnt vmcnt(1)
	v_mfma_f32_16x16x32_bf16 v[2:5], v[210:213], v[176:179], v[104:107]
	s_waitcnt vmcnt(0)
	v_mfma_f32_16x16x32_bf16 v[10:13], v[214:217], v[176:179], v[108:111]
	v_sub_u32_e32 v70, v79, v81
	v_mul_lo_u32 v70, v70, s4
	v_add_u32_e32 v74, s3, v70
	v_add_u32_e32 v83, v74, v85
	v_add_u32_e32 v70, 0x200, v83
	v_add_u32_e32 v95, v74, v78
	ds_read2_b32 v[72:73], v70 offset0:104 offset1:135
	v_add_u32_e32 v70, 0x200, v95
	ds_read2_b32 v[84:85], v70 offset0:104 offset1:135
	v_add_u32_e32 v98, v74, v87
	v_add_u32_e32 v99, v74, v92
	s_waitcnt lgkmcnt(1)
	v_fmamk_f32 v62, v62, 0x3e000000, v72
	v_cndmask_b32_e32 v62, v241, v62, vcc
	s_waitcnt lgkmcnt(0)
	v_fmamk_f32 v63, v63, 0x3e000000, v84
	v_add_u32_e32 v84, v74, v80
	v_add_u32_e32 v71, 0x200, v84
	ds_read2_b32 v[80:81], v71 offset0:104 offset1:135
	v_cndmask_b32_e64 v63, v241, v63, s[40:41]
	v_max3_f32 v70, v62, s15, v63
	v_add_u32_e32 v100, v74, v94
	v_add_u32_e32 v104, 0x400, v83
	s_waitcnt lgkmcnt(0)
	v_fmamk_f32 v64, v64, 0x3e000000, v80
	v_add_u32_e32 v80, v74, v86
	v_add_u32_e32 v71, 0x200, v80
	ds_read2_b32 v[88:89], v71 offset0:104 offset1:135
	v_cndmask_b32_e64 v64, v241, v64, s[42:43]
	v_add_u32_e32 v105, 0x400, v95
	v_add_u32_e32 v106, 0x400, v80
	v_fmac_f32_e32 v73, 0x3e000000, v54
	s_waitcnt lgkmcnt(0)
	v_fmamk_f32 v65, v65, 0x3e000000, v88
	v_cndmask_b32_e64 v65, v241, v65, s[44:45]
	v_max3_f32 v72, v70, v64, v65
	v_add_u32_e32 v70, 0x200, v98
	ds_read2_b32 v[86:87], v70 offset0:104 offset1:135
	v_fmac_f32_e32 v89, 0x3e000000, v57
	v_fmac_f32_e32 v85, 0x3e000000, v55
	v_cndmask_b32_e64 v55, v241, v89, s[44:45]
	ds_read2_b32 v[88:89], v106 offset0:38 offset1:69
	s_waitcnt lgkmcnt(1)
	v_fmamk_f32 v50, v50, 0x3e000000, v86
	v_cndmask_b32_e64 v70, v241, v50, s[46:47]
	v_add_u32_e32 v50, 0x200, v99
	ds_read2_b32 v[96:97], v50 offset0:104 offset1:135
	v_fmac_f32_e32 v87, 0x3e000000, v58
	v_fmac_f32_e32 v81, 0x3e000000, v56
	v_cndmask_b32_e64 v54, v241, v81, s[42:43]
	s_waitcnt lgkmcnt(1)
	v_fmamk_f32 v49, v49, 0x3e000000, v88
	s_waitcnt lgkmcnt(0)
	v_fmamk_f32 v50, v51, 0x3e000000, v96
	v_add_u32_e32 v96, v74, v93
	v_cndmask_b32_e64 v71, v241, v50, s[48:49]
	v_add_u32_e32 v50, 0x200, v96
	ds_read2_b32 v[50:51], v50 offset0:104 offset1:135
	v_max3_f32 v78, v72, v70, v71
	v_fmac_f32_e32 v97, 0x3e000000, v59
	ds_read2_b32 v[58:59], v104 offset0:38 offset1:69
	v_add_u32_e32 v107, 0x400, v99
	s_waitcnt lgkmcnt(1)
	v_fmamk_f32 v50, v52, 0x3e000000, v50
	v_cndmask_b32_e64 v72, v241, v50, s[50:51]
	v_add_u32_e32 v50, 0x200, v100
	ds_read2_b32 v[92:93], v50 offset0:104 offset1:135
	v_fmac_f32_e32 v51, 0x3e000000, v60
	v_cndmask_b32_e64 v52, v241, v97, s[48:49]
	v_cndmask_b32_e64 v51, v241, v51, s[50:51]
	s_waitcnt lgkmcnt(1)
	v_fmamk_f32 v46, v46, 0x3e000000, v58
	s_waitcnt lgkmcnt(0)
	v_fmamk_f32 v50, v53, 0x3e000000, v92
	v_fmac_f32_e32 v93, 0x3e000000, v61
	ds_read2_b32 v[60:61], v105 offset0:38 offset1:69
	v_cndmask_b32_e64 v75, v241, v50, s[52:53]
	v_max3_f32 v50, v78, v72, v75
	v_cndmask_b32_e32 v78, v241, v73, vcc
	v_cndmask_b32_e64 v73, v241, v85, s[40:41]
	v_max3_f32 v50, v50, v78, v73
	v_max3_f32 v50, v50, v54, v55
	v_cndmask_b32_e64 v53, v241, v87, s[46:47]
	v_max3_f32 v56, v50, v53, v52
	v_cndmask_b32_e64 v50, v241, v93, s[52:53]
	s_waitcnt lgkmcnt(0)
	v_fmamk_f32 v47, v47, 0x3e000000, v60
	v_max3_f32 v56, v56, v51, v50
	v_cndmask_b32_e32 v46, v241, v46, vcc
	v_cndmask_b32_e64 v57, v241, v47, s[40:41]
	v_max3_f32 v47, v56, v46, v57
	v_add_u32_e32 v56, 0x400, v84
	v_cndmask_b32_e64 v60, v241, v49, s[44:45]
	v_add_u32_e32 v49, 0x400, v98
	ds_read2_b32 v[86:87], v56 offset0:38 offset1:69
	ds_read2_b32 v[92:93], v49 offset0:38 offset1:69
	ds_read2_b32 v[94:95], v107 offset0:38 offset1:69
	v_add_u32_e32 v108, 0x400, v100
	ds_read2_b32 v[98:99], v108 offset0:38 offset1:69
	s_waitcnt lgkmcnt(3)
	v_fmamk_f32 v48, v48, 0x3e000000, v86
	s_waitcnt lgkmcnt(2)
	v_fmamk_f32 v34, v34, 0x3e000000, v92
	v_cndmask_b32_e64 v48, v241, v48, s[42:43]
	v_cndmask_b32_e64 v74, v241, v34, s[46:47]
	s_waitcnt lgkmcnt(1)
	v_fmamk_f32 v34, v35, 0x3e000000, v94
	v_max3_f32 v47, v47, v48, v60
	v_cndmask_b32_e64 v81, v241, v34, s[48:49]
	v_max3_f32 v34, v47, v74, v81
	v_add_u32_e32 v47, 0x400, v96
	ds_read2_b32 v[96:97], v47 offset0:38 offset1:69
	v_fmac_f32_e32 v59, 0x3e000000, v38
	v_cndmask_b32_e32 v84, v241, v59, vcc
	v_fmac_f32_e32 v93, 0x3e000000, v30
	ds_read2_b32 v[58:59], v104 offset0:100 offset1:131
	s_waitcnt lgkmcnt(1)
; __device__ __forceinline__ void mixC_mfma_unit(const bf16* Z, bf16* Yc, const float* rpb, LAS unsigned char* lds, int u, int S, int tid) {
;     ...
;     for (int t = 0; t < 16; ++t)
; #pragma unroll
;         for (int j = 0; j < 4; ++j) {
;             const int kr = rs + (t >> 1), kc = cbs + (t & 1) * 16 + 4 * q + j;
;             const bool valid = (kc >= cs) && (kc < cs + 16);
;             int dc = kc - qc + 15; dc = dc < 0 ? 0 : (dc > 30 ? 30 : dc);
;             const float sc = s[t][j] * 0.125f + rbp[(kr - qr + 7) * 31 + dc];
;             s[t][j] = valid ? sc : -1e30f; m = fmaxf(m, s[t][j]);
;         }
;     m = fmaxf(m, __shfl_xor(m, 16)); m = fmaxf(m, __shfl_xor(m, 32));
	v_fmamk_f32 v35, v36, 0x3e000000, v96
	v_cndmask_b32_e64 v80, v241, v35, s[50:51]
	v_fmamk_f32 v35, v37, 0x3e000000, v98
	v_cndmask_b32_e64 v37, v241, v93, s[46:47]
	ds_read2_b32 v[92:93], v105 offset0:100 offset1:131
	v_cndmask_b32_e64 v85, v241, v35, s[52:53]
	v_fmac_f32_e32 v61, 0x3e000000, v39
	v_max3_f32 v34, v34, v80, v85
	v_cndmask_b32_e64 v83, v241, v61, s[40:41]
	v_fmac_f32_e32 v87, 0x3e000000, v40
	v_fmac_f32_e32 v89, 0x3e000000, v41
	v_max3_f32 v34, v34, v84, v83
	v_cndmask_b32_e64 v38, v241, v87, s[42:43]
	v_cndmask_b32_e64 v40, v241, v89, s[44:45]
	v_fmac_f32_e32 v95, 0x3e000000, v31
	v_max3_f32 v34, v34, v38, v40
	v_cndmask_b32_e64 v35, v241, v95, s[48:49]
	v_fmac_f32_e32 v99, 0x3e000000, v33
	s_waitcnt lgkmcnt(1)
	v_fmamk_f32 v33, v42, 0x3e000000, v58
	v_max3_f32 v31, v34, v37, v35
	v_cndmask_b32_e32 v34, v241, v33, vcc
	s_waitcnt lgkmcnt(0)
	v_fmamk_f32 v33, v43, 0x3e000000, v92
	ds_read2_b32 v[42:43], v56 offset0:100 offset1:131
	v_fmac_f32_e32 v97, 0x3e000000, v32
	ds_read2_b32 v[94:95], v106 offset0:100 offset1:131
	v_cndmask_b32_e64 v32, v241, v97, s[50:51]
	v_cndmask_b32_e64 v30, v241, v99, s[52:53]
	ds_read2_b32 v[96:97], v49 offset0:100 offset1:131
	ds_read2_b32 v[98:99], v107 offset0:100 offset1:131
	ds_read2_b32 v[100:101], v47 offset0:100 offset1:131
	ds_read2_b32 v[102:103], v108 offset0:100 offset1:131
	v_cndmask_b32_e64 v36, v241, v33, s[40:41]
	s_waitcnt lgkmcnt(5)
	v_fmamk_f32 v33, v44, 0x3e000000, v42
	v_max3_f32 v31, v31, v32, v30
	v_cndmask_b32_e64 v42, v241, v33, s[42:43]
	s_waitcnt lgkmcnt(4)
	v_fmamk_f32 v33, v45, 0x3e000000, v94
	v_max3_f32 v31, v31, v34, v36
	v_cndmask_b32_e64 v44, v241, v33, s[44:45]
	s_waitcnt lgkmcnt(3)
	v_fmamk_f32 v26, v26, 0x3e000000, v96
	s_waitcnt lgkmcnt(2)
	v_fmamk_f32 v27, v27, 0x3e000000, v98
	s_waitcnt lgkmcnt(1)
	v_fmamk_f32 v28, v28, 0x3e000000, v100
	v_max3_f32 v31, v31, v42, v44
	v_cndmask_b32_e64 v26, v241, v26, s[46:47]
	v_cndmask_b32_e64 v86, v241, v27, s[48:49]
	v_cndmask_b32_e64 v87, v241, v28, s[50:51]
	s_waitcnt lgkmcnt(0)
	v_fmamk_f32 v28, v29, 0x3e000000, v102
	v_max3_f32 v27, v31, v26, v86
	v_cndmask_b32_e64 v89, v241, v28, s[52:53]
	v_fmac_f32_e32 v59, 0x3e000000, v22
	v_fmac_f32_e32 v93, 0x3e000000, v23
	v_max3_f32 v27, v27, v87, v89
	v_cndmask_b32_e32 v88, v241, v59, vcc
	v_cndmask_b32_e64 v29, v241, v93, s[40:41]
	v_fmac_f32_e32 v43, 0x3e000000, v24
	v_fmac_f32_e32 v95, 0x3e000000, v25
	v_max3_f32 v22, v27, v88, v29
	v_cndmask_b32_e64 v24, v241, v43, s[42:43]
	v_cndmask_b32_e64 v28, v241, v95, s[44:45]
	v_fmac_f32_e32 v97, 0x3e000000, v18
	v_fmac_f32_e32 v99, 0x3e000000, v19
	ds_read2_b32 v[58:59], v104 offset0:162 offset1:193
	ds_read2_b32 v[94:95], v105 offset0:162 offset1:193
	v_max3_f32 v25, v22, v24, v28
	v_cndmask_b32_e64 v23, v241, v97, s[46:47]
	v_cndmask_b32_e64 v22, v241, v99, s[48:49]
	v_fmac_f32_e32 v101, 0x3e000000, v20
	v_fmac_f32_e32 v103, 0x3e000000, v21
	ds_read2_b32 v[96:97], v56 offset0:162 offset1:193
	ds_read2_b32 v[98:99], v106 offset0:162 offset1:193
	v_cndmask_b32_e64 v19, v241, v101, s[50:51]
	v_cndmask_b32_e64 v18, v241, v103, s[52:53]
	ds_read2_b32 v[100:101], v49 offset0:162 offset1:193
	ds_read2_b32 v[102:103], v107 offset0:162 offset1:193
	ds_read2_b32 v[104:105], v47 offset0:162 offset1:193
	ds_read2_b32 v[106:107], v108 offset0:162 offset1:193
	v_max3_f32 v25, v25, v23, v22
	s_waitcnt lgkmcnt(7)
	v_fmamk_f32 v14, v14, 0x3e000000, v58
	s_waitcnt lgkmcnt(6)
	v_fmamk_f32 v15, v15, 0x3e000000, v94
	v_max3_f32 v20, v25, v19, v18
	v_cndmask_b32_e32 v14, v241, v14, vcc
	v_cndmask_b32_e64 v15, v241, v15, s[40:41]
	s_waitcnt lgkmcnt(5)
	v_fmamk_f32 v16, v16, 0x3e000000, v96
	s_waitcnt lgkmcnt(4)
	v_fmamk_f32 v17, v17, 0x3e000000, v98
	v_max3_f32 v20, v20, v14, v15
	v_cndmask_b32_e64 v16, v241, v16, s[42:43]
	v_cndmask_b32_e64 v21, v241, v17, s[44:45]
	s_waitcnt lgkmcnt(3)
	v_fmamk_f32 v6, v6, 0x3e000000, v100
	s_waitcnt lgkmcnt(2)
	v_fmamk_f32 v7, v7, 0x3e000000, v102
	v_max3_f32 v17, v20, v16, v21
	v_cndmask_b32_e64 v6, v241, v6, s[46:47]
	v_cndmask_b32_e64 v7, v241, v7, s[48:49]
	s_waitcnt lgkmcnt(1)
	v_fmamk_f32 v8, v8, 0x3e000000, v104
	s_waitcnt lgkmcnt(0)
	v_fmamk_f32 v9, v9, 0x3e000000, v106
	v_max3_f32 v17, v17, v6, v7
	v_cndmask_b32_e64 v8, v241, v8, s[50:51]
	v_cndmask_b32_e64 v93, v241, v9, s[52:53]
	v_fmac_f32_e32 v59, 0x3e000000, v2
	v_fmac_f32_e32 v95, 0x3e000000, v3
	v_max3_f32 v17, v17, v8, v93
	v_cndmask_b32_e32 v94, v241, v59, vcc
	v_cndmask_b32_e64 v9, v241, v95, s[40:41]
	v_fmac_f32_e32 v97, 0x3e000000, v4
	v_fmac_f32_e32 v99, 0x3e000000, v5
	v_max3_f32 v2, v17, v94, v9
	v_cndmask_b32_e64 v92, v241, v97, s[42:43]
	v_cndmask_b32_e64 v5, v241, v99, s[44:45]
	v_fmac_f32_e32 v101, 0x3e000000, v10
	v_fmac_f32_e32 v103, 0x3e000000, v11
	v_max3_f32 v2, v2, v92, v5
	v_cndmask_b32_e64 v10, v241, v101, s[46:47]
	v_cndmask_b32_e64 v3, v241, v103, s[48:49]
	v_fmac_f32_e32 v105, 0x3e000000, v12
	v_fmac_f32_e32 v107, 0x3e000000, v13
	v_max3_f32 v11, v2, v10, v3
	v_cndmask_b32_e64 v4, v241, v105, s[50:51]
	v_cndmask_b32_e64 v2, v241, v107, s[52:53]
	v_max3_f32 v11, v11, v4, v2
	ds_bpermute_b32 v12, v69, v11
	s_add_i32 s14, s14, s98
	s_mov_b32 s84, 0xf149f2ca
	s_cmpk_gt_i32 s14, 0x9ff
	s_waitcnt lgkmcnt(0)
	v_max_f32_e32 v12, v12, v12
	v_max_f32_e32 v11, v11, v12
	ds_bpermute_b32 v12, v82, v11
	s_waitcnt lgkmcnt(0)
; __device__ __forceinline__ void mixC_mfma_unit(const bf16* Z, bf16* Yc, const float* rpb, LAS unsigned char* lds, int u, int S, int tid) {
;     ...
;     m = fmaxf(m, __shfl_xor(m, 16)); m = fmaxf(m, __shfl_xor(m, 32));
;     float l = 0.f;
; #pragma unroll
;     for (int t = 0; t < 16; ++t)
; #pragma unroll
;         for (int j = 0; j < 4; ++j) { const float pe = __expf(s[t][j] - m); s[t][j] = pe; l += pe; }
;     l += __shfl_xor(l, 16); l += __shfl_xor(l, 32);
	v_max_f32_e32 v12, v12, v12
	v_max_f32_e32 v13, v11, v12
	v_sub_f32_e32 v12, v63, v13
	v_mul_f32_e32 v12, 0x3fb8aa3b, v12
	v_exp_f32_e32 v59, v12
	v_sub_f32_e32 v12, v64, v13
	v_mul_f32_e32 v12, 0x3fb8aa3b, v12
	v_sub_f32_e32 v11, v62, v13
	v_exp_f32_e32 v62, v12
	v_sub_f32_e32 v12, v65, v13
	v_mul_f32_e32 v12, 0x3fb8aa3b, v12
	v_exp_f32_e32 v63, v12
	v_sub_f32_e32 v12, v70, v13
	v_mul_f32_e32 v12, 0x3fb8aa3b, v12
	v_exp_f32_e32 v65, v12
	v_sub_f32_e32 v12, v71, v13
	v_mul_f32_e32 v12, 0x3fb8aa3b, v12
	v_exp_f32_e32 v71, v12
	v_sub_f32_e32 v12, v72, v13
	v_mul_f32_e32 v12, 0x3fb8aa3b, v12
	v_exp_f32_e32 v72, v12
	v_sub_f32_e32 v12, v75, v13
	v_mul_f32_e32 v12, 0x3fb8aa3b, v12
	v_exp_f32_e32 v75, v12
	v_sub_f32_e32 v12, v78, v13
	v_mul_f32_e32 v12, 0x3fb8aa3b, v12
	v_exp_f32_e32 v47, v12
	v_sub_f32_e32 v12, v73, v13
	v_mul_f32_e32 v12, 0x3fb8aa3b, v12
	v_exp_f32_e32 v49, v12
	v_sub_f32_e32 v12, v54, v13
	v_mul_f32_e32 v12, 0x3fb8aa3b, v12
	v_exp_f32_e32 v54, v12
	v_sub_f32_e32 v12, v55, v13
	v_mul_f32_e32 v12, 0x3fb8aa3b, v12
	v_exp_f32_e32 v55, v12
	v_sub_f32_e32 v12, v53, v13
	v_mul_f32_e32 v12, 0x3fb8aa3b, v12
	v_exp_f32_e32 v58, v12
	v_sub_f32_e32 v12, v52, v13
	v_mul_f32_e32 v12, 0x3fb8aa3b, v12
	v_exp_f32_e32 v61, v12
	v_sub_f32_e32 v12, v51, v13
	v_mul_f32_e32 v12, 0x3fb8aa3b, v12
	v_exp_f32_e32 v64, v12
	v_sub_f32_e32 v12, v50, v13
	v_mul_f32_e32 v12, 0x3fb8aa3b, v12
	v_exp_f32_e32 v70, v12
	v_sub_f32_e32 v12, v46, v13
	v_mul_f32_e32 v12, 0x3fb8aa3b, v12
	v_exp_f32_e32 v39, v12
	v_sub_f32_e32 v12, v57, v13
	v_mul_f32_e32 v12, 0x3fb8aa3b, v12
	v_exp_f32_e32 v41, v12
	v_sub_f32_e32 v12, v48, v13
	v_mul_f32_e32 v12, 0x3fb8aa3b, v12
	v_exp_f32_e32 v46, v12
	v_sub_f32_e32 v12, v60, v13
	v_mul_f32_e32 v12, 0x3fb8aa3b, v12
	v_exp_f32_e32 v48, v12
	v_sub_f32_e32 v12, v74, v13
	v_mul_f32_e32 v12, 0x3fb8aa3b, v12
	v_exp_f32_e32 v51, v12
	v_sub_f32_e32 v12, v81, v13
	v_mul_f32_e32 v12, 0x3fb8aa3b, v12
	v_exp_f32_e32 v53, v12
	v_sub_f32_e32 v12, v80, v13
	v_mul_f32_e32 v12, 0x3fb8aa3b, v12
	v_exp_f32_e32 v57, v12
	v_sub_f32_e32 v12, v85, v13
	v_mul_f32_e32 v12, 0x3fb8aa3b, v12
	v_exp_f32_e32 v60, v12
	v_sub_f32_e32 v12, v84, v13
	v_mul_f32_e32 v12, 0x3fb8aa3b, v12
	v_exp_f32_e32 v31, v12
	v_sub_f32_e32 v12, v83, v13
	v_mul_f32_e32 v12, 0x3fb8aa3b, v12
	v_mul_f32_e32 v11, 0x3fb8aa3b, v11
	v_exp_f32_e32 v33, v12
	v_sub_f32_e32 v12, v38, v13
	v_exp_f32_e32 v56, v11
	v_mul_f32_e32 v12, 0x3fb8aa3b, v12
	v_exp_f32_e32 v38, v12
	v_sub_f32_e32 v12, v40, v13
	v_mul_f32_e32 v12, 0x3fb8aa3b, v12
	v_exp_f32_e32 v40, v12
	v_sub_f32_e32 v12, v37, v13
	v_add_f32_e32 v11, 0, v56
	v_mul_f32_e32 v12, 0x3fb8aa3b, v12
	v_add_f32_e32 v11, v59, v11
	v_exp_f32_e32 v43, v12
	v_sub_f32_e32 v12, v35, v13
	v_add_f32_e32 v11, v62, v11
	v_mul_f32_e32 v12, 0x3fb8aa3b, v12
	v_add_f32_e32 v11, v63, v11
	v_exp_f32_e32 v45, v12
	v_sub_f32_e32 v12, v32, v13
	v_add_f32_e32 v11, v65, v11
	v_mul_f32_e32 v12, 0x3fb8aa3b, v12
	v_add_f32_e32 v11, v71, v11
	v_exp_f32_e32 v50, v12
	v_sub_f32_e32 v12, v30, v13
	v_add_f32_e32 v11, v72, v11
	v_mul_f32_e32 v12, 0x3fb8aa3b, v12
	v_add_f32_e32 v11, v75, v11
	v_exp_f32_e32 v52, v12
	v_sub_f32_e32 v12, v34, v13
	v_add_f32_e32 v11, v47, v11
	v_mul_f32_e32 v12, 0x3fb8aa3b, v12
	v_add_f32_e32 v11, v49, v11
	v_exp_f32_e32 v25, v12
	v_sub_f32_e32 v12, v36, v13
	v_add_f32_e32 v11, v54, v11
	v_mul_f32_e32 v12, 0x3fb8aa3b, v12
	v_add_f32_e32 v11, v55, v11
	v_exp_f32_e32 v27, v12
	v_sub_f32_e32 v12, v42, v13
	v_add_f32_e32 v11, v58, v11
	v_mul_f32_e32 v12, 0x3fb8aa3b, v12
	v_add_f32_e32 v11, v61, v11
	v_exp_f32_e32 v30, v12
	v_sub_f32_e32 v12, v44, v13
	v_add_f32_e32 v11, v64, v11
	v_mul_f32_e32 v12, 0x3fb8aa3b, v12
	v_add_f32_e32 v11, v70, v11
	v_exp_f32_e32 v32, v12
	v_sub_f32_e32 v12, v26, v13
	v_add_f32_e32 v11, v39, v11
	v_mul_f32_e32 v12, 0x3fb8aa3b, v12
	v_add_f32_e32 v11, v41, v11
	v_exp_f32_e32 v35, v12
	v_sub_f32_e32 v12, v86, v13
	v_add_f32_e32 v11, v46, v11
	v_mul_f32_e32 v12, 0x3fb8aa3b, v12
	v_add_f32_e32 v11, v48, v11
	v_exp_f32_e32 v37, v12
	v_sub_f32_e32 v12, v87, v13
	v_add_f32_e32 v11, v51, v11
	v_mul_f32_e32 v12, 0x3fb8aa3b, v12
	v_add_f32_e32 v11, v53, v11
	v_exp_f32_e32 v42, v12
	v_sub_f32_e32 v12, v89, v13
	v_add_f32_e32 v11, v57, v11
	v_mul_f32_e32 v12, 0x3fb8aa3b, v12
	v_add_f32_e32 v11, v60, v11
	v_exp_f32_e32 v44, v12
	v_sub_f32_e32 v12, v88, v13
	v_add_f32_e32 v11, v31, v11
	v_mul_f32_e32 v12, 0x3fb8aa3b, v12
	v_add_f32_e32 v11, v33, v11
	v_exp_f32_e32 v17, v12
	v_sub_f32_e32 v12, v29, v13
	v_add_f32_e32 v11, v38, v11
	v_mul_f32_e32 v12, 0x3fb8aa3b, v12
	v_add_f32_e32 v11, v40, v11
	v_exp_f32_e32 v20, v12
	v_sub_f32_e32 v12, v24, v13
	v_add_f32_e32 v11, v43, v11
	v_mul_f32_e32 v12, 0x3fb8aa3b, v12
	v_add_f32_e32 v11, v45, v11
	v_exp_f32_e32 v24, v12
	v_sub_f32_e32 v12, v28, v13
	v_add_f32_e32 v11, v50, v11
	v_mul_f32_e32 v12, 0x3fb8aa3b, v12
	v_add_f32_e32 v11, v52, v11
	v_exp_f32_e32 v26, v12
	v_sub_f32_e32 v12, v23, v13
	v_add_f32_e32 v11, v25, v11
	v_mul_f32_e32 v12, 0x3fb8aa3b, v12
	v_add_f32_e32 v11, v27, v11
	v_exp_f32_e32 v28, v12
	v_sub_f32_e32 v12, v22, v13
	v_add_f32_e32 v11, v30, v11
	v_mul_f32_e32 v12, 0x3fb8aa3b, v12
	v_add_f32_e32 v11, v32, v11
	v_exp_f32_e32 v29, v12
	v_sub_f32_e32 v12, v19, v13
	v_add_f32_e32 v11, v35, v11
	v_mul_f32_e32 v12, 0x3fb8aa3b, v12
	v_add_f32_e32 v11, v37, v11
	v_exp_f32_e32 v34, v12
	v_sub_f32_e32 v12, v18, v13
	v_add_f32_e32 v11, v42, v11
	v_mul_f32_e32 v12, 0x3fb8aa3b, v12
	v_add_f32_e32 v11, v44, v11
	v_exp_f32_e32 v36, v12
	v_sub_f32_e32 v12, v14, v13
	v_add_f32_e32 v11, v17, v11
	v_mul_f32_e32 v12, 0x3fb8aa3b, v12
	v_add_f32_e32 v11, v20, v11
	v_exp_f32_e32 v14, v12
; #define LAS __attribute__((address_space(3)))
; __device__ __forceinline__ s16x4_t trread(LAS unsigned char* p) { return __builtin_amdgcn_ds_read_tr16_b64_v4i16((LAS s16x4_t*)p); }
; __device__ __forceinline__ bf16x8_t cat4(s16x4_t a, s16x4_t b) { return (bf16x8_t){a[0], a[1], a[2], a[3], b[0], b[1], b[2], b[3]}; }
; __device__ __forceinline__ void mixC_mfma_unit(const bf16* Z, bf16* Yc, const float* rpb, LAS unsigned char* lds, int u, int S, int tid) {
;     ...
;     for (int t = 0; t < 16; ++t)
; #pragma unroll
;         for (int j = 0; j < 4; ++j) { const float pe = __expf(s[t][j] - m); s[t][j] = pe; l += pe; }
;     l += __shfl_xor(l, 16); l += __shfl_xor(l, 32);
;     f32x4 o[4];
; #pragma unroll
;     for (int dt = 0; dt < 4; ++dt) o[dt] = (f32x4){0.f, 0.f, 0.f, 0.f};
;     LAS unsigned char* vb = lds + ((rs - rb) * 64 + cbs + 4 * q + ((lane >> 2) & 3)) * KPITCH + 8 * (lane & 3);
; #pragma unroll
;     for (int G = 0; G < 8; ++G) {
;         const bf16x8_t pb = packp(s[2 * G], s[2 * G + 1]);
; #pragma unroll
;         for (int dt = 0; dt < 4; ++dt) {
;             const s16x4_t lo = trread(vb + (64 * G) * KPITCH + dt * 32), hi = trread(vb + (64 * G + 16) * KPITCH + dt * 32);
;             o[dt] = __builtin_amdgcn_mfma_f32_16x16x32_bf16(cat4(lo, hi), pb, o[dt], 0, 0, 0);
;         }
	v_sub_f32_e32 v12, v15, v13
	v_add_f32_e32 v11, v24, v11
	v_mul_f32_e32 v12, 0x3fb8aa3b, v12
	v_add_f32_e32 v11, v26, v11
	v_exp_f32_e32 v15, v12
	v_sub_f32_e32 v12, v16, v13
	v_add_f32_e32 v11, v28, v11
	v_mul_f32_e32 v12, 0x3fb8aa3b, v12
	v_add_f32_e32 v11, v29, v11
	v_exp_f32_e32 v16, v12
	v_sub_f32_e32 v12, v21, v13
	v_sub_f32_e32 v7, v7, v13
	v_add_f32_e32 v11, v34, v11
	v_mul_f32_e32 v12, 0x3fb8aa3b, v12
	v_sub_f32_e32 v6, v6, v13
	v_mul_f32_e32 v7, 0x3fb8aa3b, v7
	v_add_f32_e32 v11, v36, v11
	v_exp_f32_e32 v18, v12
	v_mul_f32_e32 v6, 0x3fb8aa3b, v6
	v_exp_f32_e32 v21, v7
	v_sub_f32_e32 v7, v8, v13
	v_add_f32_e32 v11, v14, v11
	v_exp_f32_e32 v19, v6
	v_mul_f32_e32 v7, 0x3fb8aa3b, v7
	v_add_f32_e32 v11, v15, v11
	v_exp_f32_e32 v22, v7
	v_sub_f32_e32 v7, v93, v13
	v_add_f32_e32 v11, v16, v11
	v_mul_f32_e32 v7, 0x3fb8aa3b, v7
	v_add_f32_e32 v11, v18, v11
	v_exp_f32_e32 v23, v7
	v_add_f32_e32 v6, v19, v11
	v_add_f32_e32 v6, v21, v6
	v_add_f32_e32 v6, v22, v6
	v_add_f32_e32 v7, v23, v6
	v_sub_f32_e32 v6, v94, v13
	v_mul_f32_e32 v6, 0x3fb8aa3b, v6
	v_exp_f32_e32 v6, v6
	v_sub_f32_e32 v5, v5, v13
	v_mul_f32_e32 v5, 0x3fb8aa3b, v5
	v_sub_f32_e32 v10, v10, v13
	v_add_f32_e32 v8, v6, v7
	v_sub_f32_e32 v7, v9, v13
	v_mul_f32_e32 v7, 0x3fb8aa3b, v7
	v_exp_f32_e32 v7, v7
	v_mul_f32_e32 v10, 0x3fb8aa3b, v10
	v_sub_f32_e32 v3, v3, v13
	v_exp_f32_e32 v10, v10
	v_add_f32_e32 v9, v7, v8
	v_sub_f32_e32 v8, v92, v13
	v_mul_f32_e32 v8, 0x3fb8aa3b, v8
	v_exp_f32_e32 v8, v8
	v_mul_f32_e32 v3, 0x3fb8aa3b, v3
	v_sub_f32_e32 v4, v4, v13
	v_mul_f32_e32 v4, 0x3fb8aa3b, v4
	v_add_f32_e32 v11, v8, v9
	v_exp_f32_e32 v9, v5
	v_sub_f32_e32 v2, v2, v13
	v_exp_f32_e32 v12, v4
	v_mul_f32_e32 v2, 0x3fb8aa3b, v2
	v_add_f32_e32 v5, v9, v11
	v_exp_f32_e32 v11, v3
	v_exp_f32_e32 v13, v2
	v_add_f32_e32 v5, v10, v5
	v_cvt_pk_bf16_f32 v78, v56, v59
	v_add_f32_e32 v3, v11, v5
	v_add_f32_e32 v3, v12, v3
	v_add_f32_e32 v2, v13, v3
	ds_bpermute_b32 v3, v69, v2
	s_waitcnt lgkmcnt(0)
	v_add_f32_e32 v4, v2, v3
	v_subrev_u32_e32 v2, s2, v79
	v_lshl_add_u32 v1, v2, 6, v1
	v_mad_u64_u32 v[2:3], s[2:3], v1, s67, v[68:69]
	ds_bpermute_b32 v5, v82, v4
	v_cvt_pk_bf16_f32 v79, v62, v63
	v_cvt_pk_bf16_f32 v80, v65, v71
	v_cvt_pk_bf16_f32 v81, v72, v75
	ds_read_b64_tr_b16 v[74:75], v2 offset:2304
	ds_read_b64_tr_b16 v[72:73], v2
	ds_read_b64_tr_b16 v[82:83], v2 offset:32
	ds_read_b64_tr_b16 v[84:85], v2 offset:2336
	ds_read_b64_tr_b16 v[86:87], v2 offset:64
	ds_read_b64_tr_b16 v[88:89], v2 offset:2368
	ds_read_b64_tr_b16 v[92:93], v2 offset:96
	ds_read_b64_tr_b16 v[94:95], v2 offset:2400
	s_waitcnt lgkmcnt(6)
	v_mfma_f32_16x16x32_bf16 v[72:75], v[72:75], v[78:81], 0
	v_add_u32_e32 v1, 0x10500, v2
	s_waitcnt lgkmcnt(4)
	v_mfma_f32_16x16x32_bf16 v[82:85], v[82:85], v[78:81], 0
	s_waitcnt lgkmcnt(2)
	v_mfma_f32_16x16x32_bf16 v[86:89], v[86:89], v[78:81], 0
	s_waitcnt lgkmcnt(0)
	v_mfma_f32_16x16x32_bf16 v[78:81], v[92:95], v[78:81], 0
	v_cvt_pk_bf16_f32 v92, v47, v49
	v_cvt_pk_bf16_f32 v93, v54, v55
	v_cvt_pk_bf16_f32 v94, v58, v61
	v_cvt_pk_bf16_f32 v95, v64, v70
	ds_read_b64_tr_b16 v[64:65], v2 offset:11520
	ds_read_b64_tr_b16 v[62:63], v2 offset:9216
	ds_read_b64_tr_b16 v[68:69], v2 offset:9248
	ds_read_b64_tr_b16 v[70:71], v2 offset:11552
	s_waitcnt lgkmcnt(2)
	v_mfma_f32_16x16x32_bf16 v[62:65], v[62:65], v[92:95], v[72:75]
	s_nop 2
	ds_read_b64_tr_b16 v[72:73], v2 offset:9280
	ds_read_b64_tr_b16 v[74:75], v2 offset:11584
	s_waitcnt lgkmcnt(2)
	v_mfma_f32_16x16x32_bf16 v[68:71], v[68:71], v[92:95], v[82:85]
	s_nop 2
	ds_read_b64_tr_b16 v[82:83], v2 offset:9312
	ds_read_b64_tr_b16 v[84:85], v2 offset:11616
	v_cvt_pk_bf16_f32 v54, v39, v41
	v_cvt_pk_bf16_f32 v55, v46, v48
	v_cvt_pk_bf16_f32 v56, v51, v53
	v_cvt_pk_bf16_f32 v57, v57, v60
	ds_read_b64_tr_b16 v[48:49], v2 offset:20736
	ds_read_b64_tr_b16 v[46:47], v2 offset:18432
	ds_read_b64_tr_b16 v[58:59], v2 offset:18464
	ds_read_b64_tr_b16 v[60:61], v2 offset:20768
	s_waitcnt lgkmcnt(2)
	v_mfma_f32_16x16x32_bf16 v[46:49], v[46:49], v[54:57], v[62:65]
	s_nop 2
	ds_read_b64_tr_b16 v[62:63], v2 offset:18496
	ds_read_b64_tr_b16 v[64:65], v2 offset:20800
	s_waitcnt lgkmcnt(2)
	v_mfma_f32_16x16x32_bf16 v[58:61], v[58:61], v[54:57], v[68:71]
	s_nop 2
	ds_read_b64_tr_b16 v[68:69], v2 offset:18528
	ds_read_b64_tr_b16 v[70:71], v2 offset:20832
	v_mfma_f32_16x16x32_bf16 v[72:75], v[72:75], v[92:95], v[86:89]
	v_mfma_f32_16x16x32_bf16 v[78:81], v[82:85], v[92:95], v[78:81]
	s_waitcnt lgkmcnt(2)
	v_mfma_f32_16x16x32_bf16 v[62:65], v[62:65], v[54:57], v[72:75]
	s_waitcnt lgkmcnt(0)
	v_mfma_f32_16x16x32_bf16 v[54:57], v[68:71], v[54:57], v[78:81]
	v_cvt_pk_bf16_f32 v68, v31, v33
	v_cvt_pk_bf16_f32 v69, v38, v40
	v_cvt_pk_bf16_f32 v70, v43, v45
	v_cvt_pk_bf16_f32 v71, v50, v52
	ds_read_b64_tr_b16 v[40:41], v2 offset:29952
	ds_read_b64_tr_b16 v[38:39], v2 offset:27648
	ds_read_b64_tr_b16 v[50:51], v2 offset:27680
	ds_read_b64_tr_b16 v[52:53], v2 offset:29984
	s_waitcnt lgkmcnt(2)
	v_mfma_f32_16x16x32_bf16 v[38:41], v[38:41], v[68:71], v[46:49]
	s_waitcnt lgkmcnt(0)
	v_mfma_f32_16x16x32_bf16 v[46:49], v[50:53], v[68:71], v[58:61]
	ds_read_b64_tr_b16 v[50:51], v2 offset:27712
	ds_read_b64_tr_b16 v[52:53], v2 offset:30016
	s_nop 0
	ds_read_b64_tr_b16 v[58:59], v2 offset:27744
	ds_read_b64_tr_b16 v[60:61], v2 offset:30048
	s_waitcnt lgkmcnt(0)
; __device__ __forceinline__ unsigned cvt_pk_bf16(float lo, float hi) { unsigned r; asm volatile("v_cvt_pk_bf16_f32 %0, %1, %2" : "=v"(r) : "v"(lo), "v"(hi)); return r; }
; __device__ __forceinline__ s16x4_t trread(LAS unsigned char* p) { return __builtin_amdgcn_ds_read_tr16_b64_v4i16((LAS s16x4_t*)p); }
; __device__ __forceinline__ bf16x8_t cat4(s16x4_t a, s16x4_t b) { return (bf16x8_t){a[0], a[1], a[2], a[3], b[0], b[1], b[2], b[3]}; }
; __device__ __forceinline__ void mixC_mfma_unit(const bf16* Z, bf16* Yc, const float* rpb, LAS unsigned char* lds, int u, int S, int tid) {
;     ...
;     for (int G = 0; G < 8; ++G) {
;         const bf16x8_t pb = packp(s[2 * G], s[2 * G + 1]);
; #pragma unroll
;         for (int dt = 0; dt < 4; ++dt) {
;             const s16x4_t lo = trread(vb + (64 * G) * KPITCH + dt * 32), hi = trread(vb + (64 * G + 16) * KPITCH + dt * 32);
;             o[dt] = __builtin_amdgcn_mfma_f32_16x16x32_bf16(cat4(lo, hi), pb, o[dt], 0, 0, 0);
;         }
;     }
;     const float inv = __builtin_amdgcn_rcpf(l);
;     bf16* yp = Yc + (size_t)tokc * 512 + h * 64;
; #pragma unroll
;     for (int dt = 0; dt < 4; ++dt) { uint2 wv; wv.x = pg8::cvt_pk_bf16(o[dt][0] * inv, o[dt][1] * inv); wv.y = pg8::cvt_pk_bf16(o[dt][2] * inv, o[dt][3] * inv);
;         *(uint2*)(yp + dt * 16 + 4 * q) = wv; }
;     }
; }
	v_mfma_f32_16x16x32_bf16 v[54:57], v[58:61], v[68:71], v[54:57]
	v_cvt_pk_bf16_f32 v58, v25, v27
	v_cvt_pk_bf16_f32 v59, v30, v32
	v_cvt_pk_bf16_f32 v60, v35, v37
	v_cvt_pk_bf16_f32 v61, v42, v44
	ds_read_b64_tr_b16 v[32:33], v2 offset:39168
	ds_read_b64_tr_b16 v[30:31], v2 offset:36864
	ds_read_b64_tr_b16 v[42:43], v2 offset:36896
	ds_read_b64_tr_b16 v[44:45], v2 offset:39200
	s_waitcnt lgkmcnt(2)
	v_mfma_f32_16x16x32_bf16 v[30:33], v[30:33], v[58:61], v[38:41]
	s_waitcnt lgkmcnt(0)
	v_mfma_f32_16x16x32_bf16 v[38:41], v[42:45], v[58:61], v[46:49]
	ds_read_b64_tr_b16 v[42:43], v2 offset:36928
	ds_read_b64_tr_b16 v[44:45], v2 offset:39232
	s_nop 0
	ds_read_b64_tr_b16 v[46:47], v2 offset:36960
	ds_read_b64_tr_b16 v[48:49], v2 offset:39264
	v_mfma_f32_16x16x32_bf16 v[50:53], v[50:53], v[68:71], v[62:65]
	s_waitcnt lgkmcnt(2)
	v_mfma_f32_16x16x32_bf16 v[42:45], v[42:45], v[58:61], v[50:53]
	v_cvt_pk_bf16_f32 v50, v17, v20
	v_cvt_pk_bf16_f32 v51, v24, v26
	v_cvt_pk_bf16_f32 v52, v28, v29
	v_cvt_pk_bf16_f32 v53, v34, v36
	ds_read_b64_tr_b16 v[26:27], v2 offset:48384
	ds_read_b64_tr_b16 v[24:25], v2 offset:46080
	ds_read_b64_tr_b16 v[28:29], v2 offset:46112
	s_waitcnt lgkmcnt(1)
	s_nop 1
	v_mfma_f32_16x16x32_bf16 v[24:27], v[24:27], v[50:53], v[30:33]
	s_nop 2
	ds_read_b64_tr_b16 v[30:31], v2 offset:48416
	ds_read_b64_tr_b16 v[32:33], v2 offset:46144
	ds_read_b64_tr_b16 v[34:35], v2 offset:48448
	s_waitcnt lgkmcnt(2)
	v_mfma_f32_16x16x32_bf16 v[28:31], v[28:31], v[50:53], v[38:41]
	ds_read_b64_tr_b16 v[36:37], v2 offset:46176
	s_nop 1
	ds_read_b64_tr_b16 v[38:39], v2 offset:48480
	v_cvt_pk_bf16_f32 v14, v14, v15
	v_cvt_pk_bf16_f32 v15, v16, v18
	v_cvt_pk_bf16_f32 v16, v19, v21
	v_cvt_pk_bf16_f32 v17, v22, v23
	ds_read_b64_tr_b16 v[20:21], v2 offset:57600
	ds_read_b64_tr_b16 v[18:19], v2 offset:55296
	ds_read_b64_tr_b16 v[22:23], v2 offset:55328
	s_waitcnt lgkmcnt(1)
	v_mfma_f32_16x16x32_bf16 v[18:21], v[18:21], v[14:17], v[24:27]
	s_nop 2
	ds_read_b64_tr_b16 v[24:25], v2 offset:57632
	s_waitcnt lgkmcnt(0)
	v_mfma_f32_16x16x32_bf16 v[22:25], v[22:25], v[14:17], v[28:31]
	ds_read_b64_tr_b16 v[26:27], v2 offset:55360
	s_nop 1
	ds_read_b64_tr_b16 v[28:29], v2 offset:57664
	v_mfma_f32_16x16x32_bf16 v[32:35], v[32:35], v[50:53], v[42:45]
	v_mfma_f32_16x16x32_bf16 v[46:49], v[46:49], v[58:61], v[54:57]
	s_waitcnt lgkmcnt(0)
	v_mfma_f32_16x16x32_bf16 v[26:29], v[26:29], v[14:17], v[32:35]
	ds_read_b64_tr_b16 v[30:31], v2 offset:55392
	s_nop 3
	ds_read_b64_tr_b16 v[32:33], v2 offset:57696
	v_cvt_pk_bf16_f32 v6, v6, v7
	v_cvt_pk_bf16_f32 v7, v8, v9
	v_mfma_f32_16x16x32_bf16 v[36:39], v[36:39], v[50:53], v[46:49]
	v_cvt_pk_bf16_f32 v8, v10, v11
	v_cvt_pk_bf16_f32 v9, v12, v13
	s_waitcnt lgkmcnt(0)
	v_mfma_f32_16x16x32_bf16 v[14:17], v[30:33], v[14:17], v[36:39]
	ds_read_b64_tr_b16 v[12:13], v1
	ds_read_b64_tr_b16 v[10:11], v2 offset:64512
	ds_read_b64_tr_b16 v[30:31], v2 offset:64544
	v_add_u32_e32 v1, 0x10520, v2
	ds_read_b64_tr_b16 v[32:33], v1
	v_add_u32_e32 v1, 0x10540, v2
	s_waitcnt lgkmcnt(2)
	v_mfma_f32_16x16x32_bf16 v[10:13], v[10:13], v[6:9], v[18:21]
	s_waitcnt lgkmcnt(0)
	v_mfma_f32_16x16x32_bf16 v[18:21], v[30:33], v[6:9], v[22:25]
	s_nop 2
	ds_read_b64_tr_b16 v[22:23], v2 offset:64576
	ds_read_b64_tr_b16 v[24:25], v1
	v_add_u32_e32 v1, 0x10560, v2
	s_waitcnt lgkmcnt(0)
	v_mfma_f32_16x16x32_bf16 v[22:25], v[22:25], v[6:9], v[26:29]
	s_nop 2
	ds_read_b64_tr_b16 v[26:27], v2 offset:64608
	ds_read_b64_tr_b16 v[28:29], v1
	v_add_f32_e32 v1, v4, v5
	v_rcp_f32_e32 v1, v1
	v_lshlrev_b64 v[2:3], 10, v[76:77]
	v_lshl_add_u64 v[2:3], v[66:67], 0, v[2:3]
	s_waitcnt lgkmcnt(0)
	v_mfma_f32_16x16x32_bf16 v[6:9], v[26:29], v[6:9], v[14:17]
	v_mul_f32_e32 v4, v1, v10
	v_mul_f32_e32 v5, v1, v11
	v_cvt_pk_bf16_f32 v4, v4, v5
	v_mul_f32_e32 v5, v1, v12
	v_mul_f32_e32 v10, v1, v13
	v_cvt_pk_bf16_f32 v5, v5, v10
	v_lshrrev_b32_e32 v218, 4, v231
	v_lshl_or_b32 v218, v231, 4, v218
	v_and_b32_e32 v218, 0x33, v218
	v_and_or_b32 v218, v231, 12, v218
	v_lshlrev_b32_e32 v218, 2, v218
	ds_bpermute_b32 v220, v218, v2
	ds_bpermute_b32 v221, v218, v3
	ds_bpermute_b32 v4, v218, v4
	ds_bpermute_b32 v5, v218, v5
	s_waitcnt lgkmcnt(0)
	global_store_dwordx2 v[220:221], v[4:5], off
	v_mul_f32_e32 v4, v1, v18
	v_mul_f32_e32 v5, v1, v19
	v_cvt_pk_bf16_f32 v4, v4, v5
	v_mul_f32_e32 v5, v1, v20
	v_mul_f32_e32 v10, v1, v21
	v_cvt_pk_bf16_f32 v5, v5, v10
	ds_bpermute_b32 v4, v218, v4
	ds_bpermute_b32 v5, v218, v5
	s_waitcnt lgkmcnt(0)
	global_store_dwordx2 v[220:221], v[4:5], off offset:32
	v_mul_f32_e32 v4, v1, v22
	v_mul_f32_e32 v5, v1, v23
	v_cvt_pk_bf16_f32 v4, v4, v5
	v_mul_f32_e32 v5, v1, v24
	v_mul_f32_e32 v10, v1, v25
	v_cvt_pk_bf16_f32 v5, v5, v10
	ds_bpermute_b32 v4, v218, v4
	ds_bpermute_b32 v5, v218, v5
	s_waitcnt lgkmcnt(0)
	global_store_dwordx2 v[220:221], v[4:5], off offset:64
	v_mul_f32_e32 v4, v1, v6
	v_mul_f32_e32 v5, v1, v7
	v_cvt_pk_bf16_f32 v4, v4, v5
	v_mul_f32_e32 v5, v1, v8
	v_mul_f32_e32 v1, v1, v9
	v_cvt_pk_bf16_f32 v5, v5, v1
	ds_bpermute_b32 v4, v218, v4
	ds_bpermute_b32 v5, v218, v5
	s_waitcnt lgkmcnt(0)
	global_store_dwordx2 v[220:221], v[4:5], off offset:96
	s_cbranch_scc1 .LBB0_264
